# wave-sum butterflies (conv LayerNorm stats, row-norm phases): xor 1/2/4/8 steps by DPP adds instead of ds_bpermute round trips
# speedup vs baseline: 1.0088x; 1.0011x over previous
.LBB0_1209:
	v_lshl_add_u32 v88, s26, 13, v84
	v_lshl_add_u32 v89, s27, 13, v84
	ds_read_u16 v68, v88
	ds_read_u16 v69, v89
	ds_read_u16 v70, v88 offset:1024
	ds_read_u16 v71, v89 offset:1024
	ds_read_u16 v72, v88 offset:2048
	ds_read_u16 v73, v89 offset:2048
	ds_read_u16 v74, v88 offset:3072
	ds_read_u16 v75, v89 offset:3072
	ds_read_u16 v76, v88 offset:4096
	ds_read_u16 v77, v89 offset:4096
	s_waitcnt lgkmcnt(8)
	v_lshlrev_b32_e32 v69, 16, v69
	v_lshlrev_b32_e32 v68, 16, v68
	ds_read_u16 v78, v88 offset:5120
	ds_read_u16 v79, v89 offset:5120
	v_pk_fma_f32 v[68:69], v[4:5], v[68:69], v[66:67]
	s_waitcnt lgkmcnt(8)
	v_lshlrev_b32_e32 v71, 16, v71
	v_lshlrev_b32_e32 v70, 16, v70
	ds_read_u16 v80, v88 offset:6144
	ds_read_u16 v81, v89 offset:6144
	v_pk_fma_f32 v[68:69], v[6:7], v[70:71], v[68:69]
	v_pk_fma_f32 v[70:71], v[4:5], v[70:71], v[66:67]
	s_waitcnt lgkmcnt(8)
	v_lshlrev_b32_e32 v73, 16, v73
	v_lshlrev_b32_e32 v72, 16, v72
	ds_read_u16 v82, v88 offset:7168
	ds_read_u16 v83, v89 offset:7168
	v_pk_fma_f32 v[68:69], v[8:9], v[72:73], v[68:69]
	v_pk_fma_f32 v[70:71], v[6:7], v[72:73], v[70:71]
	v_pk_fma_f32 v[72:73], v[4:5], v[72:73], v[66:67]
	s_waitcnt lgkmcnt(8)
	v_lshlrev_b32_e32 v75, 16, v75
	v_lshlrev_b32_e32 v74, 16, v74
	ds_read_u16 v86, v88 offset:8192
	ds_read_u16 v87, v89 offset:8192
	v_pk_fma_f32 v[68:69], v[10:11], v[74:75], v[68:69]
	v_pk_fma_f32 v[70:71], v[8:9], v[74:75], v[70:71]
	v_pk_fma_f32 v[72:73], v[6:7], v[74:75], v[72:73]
	v_pk_fma_f32 v[74:75], v[4:5], v[74:75], v[66:67]
	s_waitcnt lgkmcnt(8)
	v_lshlrev_b32_e32 v77, 16, v77
	v_lshlrev_b32_e32 v76, 16, v76
	v_pk_fma_f32 v[68:69], v[12:13], v[76:77], v[68:69]
	v_pk_fma_f32 v[70:71], v[10:11], v[76:77], v[70:71]
	v_pk_fma_f32 v[72:73], v[8:9], v[76:77], v[72:73]
	v_pk_fma_f32 v[74:75], v[6:7], v[76:77], v[74:75]
	v_pk_fma_f32 v[76:77], v[4:5], v[76:77], v[66:67]
	s_waitcnt lgkmcnt(6)
	v_lshlrev_b32_e32 v79, 16, v79
	v_lshlrev_b32_e32 v78, 16, v78
	v_pk_fma_f32 v[68:69], v[14:15], v[78:79], v[68:69]
	v_pk_fma_f32 v[70:71], v[12:13], v[78:79], v[70:71]
	v_pk_fma_f32 v[72:73], v[10:11], v[78:79], v[72:73]
	v_pk_fma_f32 v[74:75], v[8:9], v[78:79], v[74:75]
	v_pk_fma_f32 v[76:77], v[6:7], v[78:79], v[76:77]
	v_pk_fma_f32 v[78:79], v[4:5], v[78:79], v[66:67]
	s_waitcnt lgkmcnt(4)
	v_lshlrev_b32_e32 v81, 16, v81
	v_lshlrev_b32_e32 v80, 16, v80
	v_pk_fma_f32 v[68:69], v[16:17], v[80:81], v[68:69]
	v_pk_fma_f32 v[70:71], v[14:15], v[80:81], v[70:71]
	v_pk_fma_f32 v[72:73], v[12:13], v[80:81], v[72:73]
	v_pk_fma_f32 v[74:75], v[10:11], v[80:81], v[74:75]
	v_pk_fma_f32 v[76:77], v[8:9], v[80:81], v[76:77]
	v_pk_fma_f32 v[78:79], v[6:7], v[80:81], v[78:79]
	v_pk_fma_f32 v[80:81], v[4:5], v[80:81], v[66:67]
	s_waitcnt lgkmcnt(2)
	v_lshlrev_b32_e32 v83, 16, v83
	v_lshlrev_b32_e32 v82, 16, v82
	v_pk_fma_f32 v[68:69], v[18:19], v[82:83], v[68:69]
	v_pk_fma_f32 v[70:71], v[16:17], v[82:83], v[70:71]
	v_pk_fma_f32 v[72:73], v[14:15], v[82:83], v[72:73]
	v_pk_fma_f32 v[74:75], v[12:13], v[82:83], v[74:75]
	v_pk_fma_f32 v[76:77], v[10:11], v[82:83], v[76:77]
	v_pk_fma_f32 v[78:79], v[8:9], v[82:83], v[78:79]
	v_pk_fma_f32 v[80:81], v[6:7], v[82:83], v[80:81]
	v_pk_fma_f32 v[82:83], v[4:5], v[82:83], v[66:67]
	s_waitcnt lgkmcnt(0)
	v_lshlrev_b32_e32 v87, 16, v87
	v_lshlrev_b32_e32 v86, 16, v86
	v_pk_fma_f32 v[68:69], v[20:21], v[86:87], v[68:69]
	v_pk_fma_f32 v[70:71], v[18:19], v[86:87], v[70:71]
	v_pk_fma_f32 v[72:73], v[16:17], v[86:87], v[72:73]
	v_pk_fma_f32 v[74:75], v[14:15], v[86:87], v[74:75]
	v_pk_fma_f32 v[76:77], v[12:13], v[86:87], v[76:77]
	v_pk_fma_f32 v[78:79], v[10:11], v[86:87], v[78:79]
	v_pk_fma_f32 v[80:81], v[8:9], v[86:87], v[80:81]
	v_pk_fma_f32 v[82:83], v[6:7], v[86:87], v[82:83]
	ds_read_u16 v86, v88 offset:9216
	ds_read_u16 v87, v89 offset:9216
	s_add_i32 s28, s28, -2
	s_waitcnt lgkmcnt(1)
	v_lshlrev_b32_e32 v86, 16, v86
	s_waitcnt lgkmcnt(0)
	v_lshlrev_b32_e32 v87, 16, v87
	v_pk_fma_f32 v[68:69], v[22:23], v[86:87], v[68:69]
	v_pk_fma_f32 v[70:71], v[20:21], v[86:87], v[70:71]
	v_pk_fma_f32 v[72:73], v[18:19], v[86:87], v[72:73]
	v_pk_fma_f32 v[74:75], v[16:17], v[86:87], v[74:75]
	v_pk_fma_f32 v[76:77], v[14:15], v[86:87], v[76:77]
	v_pk_fma_f32 v[78:79], v[12:13], v[86:87], v[78:79]
	v_pk_fma_f32 v[80:81], v[10:11], v[86:87], v[80:81]
	v_pk_fma_f32 v[82:83], v[8:9], v[86:87], v[82:83]
	ds_read_u16 v86, v88 offset:10240
	ds_read_u16 v87, v89 offset:10240
	s_waitcnt lgkmcnt(1)
	v_lshlrev_b32_e32 v86, 16, v86
	s_waitcnt lgkmcnt(0)
	v_lshlrev_b32_e32 v87, 16, v87
	v_pk_fma_f32 v[68:69], v[24:25], v[86:87], v[68:69]
	v_pk_fma_f32 v[70:71], v[22:23], v[86:87], v[70:71]
	v_pk_fma_f32 v[72:73], v[20:21], v[86:87], v[72:73]
	v_pk_fma_f32 v[74:75], v[18:19], v[86:87], v[74:75]
	v_pk_fma_f32 v[76:77], v[16:17], v[86:87], v[76:77]
	v_pk_fma_f32 v[78:79], v[14:15], v[86:87], v[78:79]
	v_pk_fma_f32 v[80:81], v[12:13], v[86:87], v[80:81]
	v_pk_fma_f32 v[82:83], v[10:11], v[86:87], v[82:83]
	ds_read_u16 v86, v88 offset:11264
	ds_read_u16 v87, v89 offset:11264
	s_waitcnt lgkmcnt(1)
	v_lshlrev_b32_e32 v86, 16, v86
	s_waitcnt lgkmcnt(0)
	v_lshlrev_b32_e32 v87, 16, v87
	v_pk_fma_f32 v[68:69], v[26:27], v[86:87], v[68:69]
	v_pk_fma_f32 v[70:71], v[24:25], v[86:87], v[70:71]
	v_pk_fma_f32 v[72:73], v[22:23], v[86:87], v[72:73]
	v_pk_fma_f32 v[74:75], v[20:21], v[86:87], v[74:75]
	v_pk_fma_f32 v[76:77], v[18:19], v[86:87], v[76:77]
	v_pk_fma_f32 v[78:79], v[16:17], v[86:87], v[78:79]
	v_pk_fma_f32 v[80:81], v[14:15], v[86:87], v[80:81]
	v_pk_fma_f32 v[82:83], v[12:13], v[86:87], v[82:83]
	ds_read_u16 v86, v88 offset:12288
	ds_read_u16 v87, v89 offset:12288
	s_waitcnt lgkmcnt(1)
	v_lshlrev_b32_e32 v86, 16, v86
	s_waitcnt lgkmcnt(0)
	v_lshlrev_b32_e32 v87, 16, v87
	v_pk_fma_f32 v[68:69], v[28:29], v[86:87], v[68:69]
	v_pk_fma_f32 v[70:71], v[26:27], v[86:87], v[70:71]
	v_pk_fma_f32 v[72:73], v[24:25], v[86:87], v[72:73]
	v_pk_fma_f32 v[74:75], v[22:23], v[86:87], v[74:75]
	v_pk_fma_f32 v[76:77], v[20:21], v[86:87], v[76:77]
	v_pk_fma_f32 v[78:79], v[18:19], v[86:87], v[78:79]
	v_pk_fma_f32 v[80:81], v[16:17], v[86:87], v[80:81]
	v_pk_fma_f32 v[82:83], v[14:15], v[86:87], v[82:83]
	ds_read_u16 v86, v88 offset:13312
	ds_read_u16 v87, v89 offset:13312
	s_waitcnt lgkmcnt(1)
	v_lshlrev_b32_e32 v86, 16, v86
	s_waitcnt lgkmcnt(0)
	v_lshlrev_b32_e32 v87, 16, v87
	v_pk_fma_f32 v[68:69], v[30:31], v[86:87], v[68:69]
	v_pk_fma_f32 v[70:71], v[28:29], v[86:87], v[70:71]
	v_pk_fma_f32 v[72:73], v[26:27], v[86:87], v[72:73]
	v_pk_fma_f32 v[74:75], v[24:25], v[86:87], v[74:75]
	v_pk_fma_f32 v[76:77], v[22:23], v[86:87], v[76:77]
	v_pk_fma_f32 v[78:79], v[20:21], v[86:87], v[78:79]
	v_pk_fma_f32 v[80:81], v[18:19], v[86:87], v[80:81]
	v_pk_fma_f32 v[82:83], v[16:17], v[86:87], v[82:83]
	ds_read_u16 v86, v88 offset:14336
	ds_read_u16 v87, v89 offset:14336
	s_waitcnt lgkmcnt(1)
	v_lshlrev_b32_e32 v86, 16, v86
	s_waitcnt lgkmcnt(0)
	v_lshlrev_b32_e32 v87, 16, v87
	v_pk_fma_f32 v[68:69], v[32:33], v[86:87], v[68:69]
	v_pk_fma_f32 v[70:71], v[30:31], v[86:87], v[70:71]
	v_pk_fma_f32 v[72:73], v[28:29], v[86:87], v[72:73]
	v_pk_fma_f32 v[74:75], v[26:27], v[86:87], v[74:75]
	v_pk_fma_f32 v[76:77], v[24:25], v[86:87], v[76:77]
	v_pk_fma_f32 v[78:79], v[22:23], v[86:87], v[78:79]
	v_pk_fma_f32 v[80:81], v[20:21], v[86:87], v[80:81]
	v_pk_fma_f32 v[82:83], v[18:19], v[86:87], v[82:83]
	ds_read_u16 v86, v88 offset:15360
	ds_read_u16 v87, v89 offset:15360
	s_waitcnt lgkmcnt(1)
	v_lshlrev_b32_e32 v86, 16, v86
	s_waitcnt lgkmcnt(0)
	v_lshlrev_b32_e32 v87, 16, v87
	v_pk_fma_f32 v[68:69], v[34:35], v[86:87], v[68:69]
	v_pk_fma_f32 v[70:71], v[32:33], v[86:87], v[70:71]
	v_pk_fma_f32 v[72:73], v[30:31], v[86:87], v[72:73]
	v_pk_fma_f32 v[74:75], v[28:29], v[86:87], v[74:75]
	v_pk_fma_f32 v[76:77], v[26:27], v[86:87], v[76:77]
	v_pk_fma_f32 v[78:79], v[24:25], v[86:87], v[78:79]
	v_pk_fma_f32 v[80:81], v[22:23], v[86:87], v[80:81]
	v_pk_fma_f32 v[82:83], v[20:21], v[86:87], v[82:83]
	ds_read_u16 v86, v88 offset:16384
	ds_read_u16 v87, v89 offset:16384
	s_waitcnt lgkmcnt(1)
	v_lshlrev_b32_e32 v86, 16, v86
	s_waitcnt lgkmcnt(0)
	v_lshlrev_b32_e32 v87, 16, v87
	v_pk_fma_f32 v[68:69], v[36:37], v[86:87], v[68:69]
	v_pk_fma_f32 v[70:71], v[34:35], v[86:87], v[70:71]
	v_pk_fma_f32 v[72:73], v[32:33], v[86:87], v[72:73]
	v_pk_fma_f32 v[74:75], v[30:31], v[86:87], v[74:75]
	v_pk_fma_f32 v[76:77], v[28:29], v[86:87], v[76:77]
	v_pk_fma_f32 v[78:79], v[26:27], v[86:87], v[78:79]
	v_pk_fma_f32 v[80:81], v[24:25], v[86:87], v[80:81]
	v_pk_fma_f32 v[82:83], v[22:23], v[86:87], v[82:83]
	ds_read_u16 v86, v88 offset:17408
	ds_read_u16 v87, v89 offset:17408
	s_waitcnt lgkmcnt(1)
	v_lshlrev_b32_e32 v86, 16, v86
	s_waitcnt lgkmcnt(0)
	v_lshlrev_b32_e32 v87, 16, v87
	v_pk_fma_f32 v[68:69], v[38:39], v[86:87], v[68:69]
	v_pk_fma_f32 v[70:71], v[36:37], v[86:87], v[70:71]
	v_pk_fma_f32 v[72:73], v[34:35], v[86:87], v[72:73]
	v_pk_fma_f32 v[74:75], v[32:33], v[86:87], v[74:75]
	v_pk_fma_f32 v[76:77], v[30:31], v[86:87], v[76:77]
	v_pk_fma_f32 v[78:79], v[28:29], v[86:87], v[78:79]
	v_pk_fma_f32 v[80:81], v[26:27], v[86:87], v[80:81]
	v_pk_fma_f32 v[82:83], v[24:25], v[86:87], v[82:83]
	ds_read_u16 v86, v88 offset:18432
	ds_read_u16 v87, v89 offset:18432
	s_waitcnt lgkmcnt(1)
	v_lshlrev_b32_e32 v86, 16, v86
	s_waitcnt lgkmcnt(0)
	v_lshlrev_b32_e32 v87, 16, v87
	v_pk_fma_f32 v[68:69], v[40:41], v[86:87], v[68:69]
	v_pk_fma_f32 v[70:71], v[38:39], v[86:87], v[70:71]
	v_pk_fma_f32 v[72:73], v[36:37], v[86:87], v[72:73]
	v_pk_fma_f32 v[74:75], v[34:35], v[86:87], v[74:75]
	v_pk_fma_f32 v[76:77], v[32:33], v[86:87], v[76:77]
	v_pk_fma_f32 v[78:79], v[30:31], v[86:87], v[78:79]
	v_pk_fma_f32 v[80:81], v[28:29], v[86:87], v[80:81]
	v_pk_fma_f32 v[82:83], v[26:27], v[86:87], v[82:83]
	ds_read_u16 v86, v88 offset:19456
	ds_read_u16 v87, v89 offset:19456
	s_waitcnt lgkmcnt(1)
	v_lshlrev_b32_e32 v86, 16, v86
	s_waitcnt lgkmcnt(0)
	v_lshlrev_b32_e32 v87, 16, v87
	v_pk_fma_f32 v[68:69], v[42:43], v[86:87], v[68:69]
	v_pk_fma_f32 v[70:71], v[40:41], v[86:87], v[70:71]
	v_pk_fma_f32 v[72:73], v[38:39], v[86:87], v[72:73]
	v_pk_fma_f32 v[74:75], v[36:37], v[86:87], v[74:75]
	v_pk_fma_f32 v[76:77], v[34:35], v[86:87], v[76:77]
	v_pk_fma_f32 v[78:79], v[32:33], v[86:87], v[78:79]
	v_pk_fma_f32 v[80:81], v[30:31], v[86:87], v[80:81]
	v_pk_fma_f32 v[82:83], v[28:29], v[86:87], v[82:83]
	ds_read_u16 v86, v88 offset:20480
	ds_read_u16 v87, v89 offset:20480
	s_waitcnt lgkmcnt(1)
	v_lshlrev_b32_e32 v86, 16, v86
	s_waitcnt lgkmcnt(0)
	v_lshlrev_b32_e32 v87, 16, v87
	v_pk_fma_f32 v[68:69], v[44:45], v[86:87], v[68:69]
	v_pk_fma_f32 v[70:71], v[42:43], v[86:87], v[70:71]
	v_pk_fma_f32 v[72:73], v[40:41], v[86:87], v[72:73]
	v_pk_fma_f32 v[74:75], v[38:39], v[86:87], v[74:75]
	v_pk_fma_f32 v[76:77], v[36:37], v[86:87], v[76:77]
	v_pk_fma_f32 v[78:79], v[34:35], v[86:87], v[78:79]
	v_pk_fma_f32 v[80:81], v[32:33], v[86:87], v[80:81]
	v_pk_fma_f32 v[82:83], v[30:31], v[86:87], v[82:83]
	ds_read_u16 v86, v88 offset:21504
	ds_read_u16 v87, v89 offset:21504
	s_waitcnt lgkmcnt(1)
	v_lshlrev_b32_e32 v86, 16, v86
	s_waitcnt lgkmcnt(0)
	v_lshlrev_b32_e32 v87, 16, v87
	v_pk_fma_f32 v[68:69], v[46:47], v[86:87], v[68:69]
	v_pk_fma_f32 v[70:71], v[44:45], v[86:87], v[70:71]
	v_pk_fma_f32 v[72:73], v[42:43], v[86:87], v[72:73]
	v_pk_fma_f32 v[74:75], v[40:41], v[86:87], v[74:75]
	v_pk_fma_f32 v[76:77], v[38:39], v[86:87], v[76:77]
	v_pk_fma_f32 v[78:79], v[36:37], v[86:87], v[78:79]
	v_pk_fma_f32 v[80:81], v[34:35], v[86:87], v[80:81]
	v_pk_fma_f32 v[82:83], v[32:33], v[86:87], v[82:83]
	ds_read_u16 v86, v88 offset:22528
	ds_read_u16 v87, v89 offset:22528
	s_waitcnt lgkmcnt(1)
	v_lshlrev_b32_e32 v86, 16, v86
	s_waitcnt lgkmcnt(0)
	v_lshlrev_b32_e32 v87, 16, v87
	v_pk_fma_f32 v[68:69], v[48:49], v[86:87], v[68:69]
	v_pk_fma_f32 v[70:71], v[46:47], v[86:87], v[70:71]
	v_pk_fma_f32 v[72:73], v[44:45], v[86:87], v[72:73]
	v_pk_fma_f32 v[74:75], v[42:43], v[86:87], v[74:75]
	v_pk_fma_f32 v[76:77], v[40:41], v[86:87], v[76:77]
	v_pk_fma_f32 v[78:79], v[38:39], v[86:87], v[78:79]
	v_pk_fma_f32 v[80:81], v[36:37], v[86:87], v[80:81]
	v_pk_fma_f32 v[82:83], v[34:35], v[86:87], v[82:83]
	ds_read_u16 v86, v88 offset:23552
	ds_read_u16 v87, v89 offset:23552
	s_waitcnt lgkmcnt(1)
	v_lshlrev_b32_e32 v86, 16, v86
	s_waitcnt lgkmcnt(0)
	v_lshlrev_b32_e32 v87, 16, v87
	v_pk_fma_f32 v[68:69], v[50:51], v[86:87], v[68:69]
	v_pk_fma_f32 v[70:71], v[48:49], v[86:87], v[70:71]
	v_pk_fma_f32 v[72:73], v[46:47], v[86:87], v[72:73]
	v_pk_fma_f32 v[74:75], v[44:45], v[86:87], v[74:75]
	v_pk_fma_f32 v[76:77], v[42:43], v[86:87], v[76:77]
	v_pk_fma_f32 v[78:79], v[40:41], v[86:87], v[78:79]
	v_pk_fma_f32 v[80:81], v[38:39], v[86:87], v[80:81]
	v_pk_fma_f32 v[82:83], v[36:37], v[86:87], v[82:83]
	ds_read_u16 v86, v88 offset:24576
	ds_read_u16 v87, v89 offset:24576
	s_waitcnt lgkmcnt(1)
	v_lshlrev_b32_e32 v86, 16, v86
	s_waitcnt lgkmcnt(0)
	v_lshlrev_b32_e32 v87, 16, v87
	v_pk_fma_f32 v[68:69], v[52:53], v[86:87], v[68:69]
	v_pk_fma_f32 v[70:71], v[50:51], v[86:87], v[70:71]
	v_pk_fma_f32 v[72:73], v[48:49], v[86:87], v[72:73]
	v_pk_fma_f32 v[74:75], v[46:47], v[86:87], v[74:75]
	v_pk_fma_f32 v[76:77], v[44:45], v[86:87], v[76:77]
	v_pk_fma_f32 v[78:79], v[42:43], v[86:87], v[78:79]
	v_pk_fma_f32 v[80:81], v[40:41], v[86:87], v[80:81]
	v_pk_fma_f32 v[82:83], v[38:39], v[86:87], v[82:83]
	ds_read_u16 v86, v88 offset:25600
	ds_read_u16 v87, v89 offset:25600
	s_waitcnt lgkmcnt(1)
	v_lshlrev_b32_e32 v86, 16, v86
	s_waitcnt lgkmcnt(0)
	v_lshlrev_b32_e32 v87, 16, v87
	v_pk_fma_f32 v[68:69], v[54:55], v[86:87], v[68:69]
	v_pk_fma_f32 v[70:71], v[52:53], v[86:87], v[70:71]
	v_pk_fma_f32 v[72:73], v[50:51], v[86:87], v[72:73]
	v_pk_fma_f32 v[74:75], v[48:49], v[86:87], v[74:75]
	v_pk_fma_f32 v[76:77], v[46:47], v[86:87], v[76:77]
	v_pk_fma_f32 v[78:79], v[44:45], v[86:87], v[78:79]
	v_pk_fma_f32 v[80:81], v[42:43], v[86:87], v[80:81]
	v_pk_fma_f32 v[82:83], v[40:41], v[86:87], v[82:83]
	ds_read_u16 v86, v88 offset:26624
	ds_read_u16 v87, v89 offset:26624
	s_waitcnt lgkmcnt(1)
	v_lshlrev_b32_e32 v86, 16, v86
	s_waitcnt lgkmcnt(0)
	v_lshlrev_b32_e32 v87, 16, v87
	v_pk_fma_f32 v[68:69], v[56:57], v[86:87], v[68:69]
	v_pk_fma_f32 v[70:71], v[54:55], v[86:87], v[70:71]
	v_pk_fma_f32 v[72:73], v[52:53], v[86:87], v[72:73]
	v_pk_fma_f32 v[74:75], v[50:51], v[86:87], v[74:75]
	v_pk_fma_f32 v[76:77], v[48:49], v[86:87], v[76:77]
	v_pk_fma_f32 v[78:79], v[46:47], v[86:87], v[78:79]
	v_pk_fma_f32 v[80:81], v[44:45], v[86:87], v[80:81]
	v_pk_fma_f32 v[82:83], v[42:43], v[86:87], v[82:83]
	ds_read_u16 v86, v88 offset:27648
	ds_read_u16 v87, v89 offset:27648
	s_waitcnt lgkmcnt(1)
	v_lshlrev_b32_e32 v86, 16, v86
	s_waitcnt lgkmcnt(0)
	v_lshlrev_b32_e32 v87, 16, v87
	v_pk_fma_f32 v[68:69], v[58:59], v[86:87], v[68:69]
	v_pk_fma_f32 v[70:71], v[56:57], v[86:87], v[70:71]
	v_pk_fma_f32 v[72:73], v[54:55], v[86:87], v[72:73]
	v_pk_fma_f32 v[74:75], v[52:53], v[86:87], v[74:75]
	v_pk_fma_f32 v[76:77], v[50:51], v[86:87], v[76:77]
	v_pk_fma_f32 v[78:79], v[48:49], v[86:87], v[78:79]
	v_pk_fma_f32 v[80:81], v[46:47], v[86:87], v[80:81]
	v_pk_fma_f32 v[82:83], v[44:45], v[86:87], v[82:83]
	ds_read_u16 v86, v88 offset:28672
	ds_read_u16 v87, v89 offset:28672
	s_waitcnt lgkmcnt(1)
	v_lshlrev_b32_e32 v86, 16, v86
	s_waitcnt lgkmcnt(0)
	v_lshlrev_b32_e32 v87, 16, v87
	v_pk_fma_f32 v[68:69], v[60:61], v[86:87], v[68:69]
	v_pk_fma_f32 v[70:71], v[58:59], v[86:87], v[70:71]
	v_pk_fma_f32 v[72:73], v[56:57], v[86:87], v[72:73]
	v_pk_fma_f32 v[74:75], v[54:55], v[86:87], v[74:75]
	v_pk_fma_f32 v[76:77], v[52:53], v[86:87], v[76:77]
	v_pk_fma_f32 v[78:79], v[50:51], v[86:87], v[78:79]
	v_pk_fma_f32 v[80:81], v[48:49], v[86:87], v[80:81]
	v_pk_fma_f32 v[82:83], v[46:47], v[86:87], v[82:83]
	ds_read_u16 v86, v88 offset:29696
	ds_read_u16 v87, v89 offset:29696
	s_waitcnt lgkmcnt(1)
	v_lshlrev_b32_e32 v86, 16, v86
	s_waitcnt lgkmcnt(0)
	v_lshlrev_b32_e32 v87, 16, v87
	v_pk_fma_f32 v[68:69], v[62:63], v[86:87], v[68:69]
	v_pk_fma_f32 v[70:71], v[60:61], v[86:87], v[70:71]
	v_pk_fma_f32 v[72:73], v[58:59], v[86:87], v[72:73]
	v_pk_fma_f32 v[74:75], v[56:57], v[86:87], v[74:75]
	v_pk_fma_f32 v[76:77], v[54:55], v[86:87], v[76:77]
	v_pk_fma_f32 v[78:79], v[52:53], v[86:87], v[78:79]
	v_pk_fma_f32 v[80:81], v[50:51], v[86:87], v[80:81]
	v_pk_fma_f32 v[82:83], v[48:49], v[86:87], v[82:83]
	ds_read_u16 v86, v88 offset:30720
	ds_read_u16 v87, v89 offset:30720
	s_waitcnt lgkmcnt(1)
	v_lshlrev_b32_e32 v86, 16, v86
	s_waitcnt lgkmcnt(0)
	v_lshlrev_b32_e32 v87, 16, v87
	v_pk_fma_f32 v[68:69], v[64:65], v[86:87], v[68:69]
	v_pk_fma_f32 v[70:71], v[62:63], v[86:87], v[70:71]
	v_pk_fma_f32 v[72:73], v[60:61], v[86:87], v[72:73]
	v_pk_fma_f32 v[74:75], v[58:59], v[86:87], v[74:75]
	v_pk_fma_f32 v[76:77], v[56:57], v[86:87], v[76:77]
	v_pk_fma_f32 v[78:79], v[54:55], v[86:87], v[78:79]
	v_pk_fma_f32 v[80:81], v[52:53], v[86:87], v[80:81]
	v_pk_fma_f32 v[82:83], v[50:51], v[86:87], v[82:83]
	ds_read_u16 v86, v88 offset:31744
	ds_read_u16 v87, v89 offset:31744
	s_waitcnt lgkmcnt(1)
	v_lshlrev_b32_e32 v86, 16, v86
	s_waitcnt lgkmcnt(0)
	v_lshlrev_b32_e32 v87, 16, v87
	v_pk_fma_f32 v[70:71], v[64:65], v[86:87], v[70:71]
	v_pk_fma_f32 v[72:73], v[62:63], v[86:87], v[72:73]
	v_pk_fma_f32 v[74:75], v[60:61], v[86:87], v[74:75]
	v_pk_fma_f32 v[76:77], v[58:59], v[86:87], v[76:77]
	v_pk_fma_f32 v[78:79], v[56:57], v[86:87], v[78:79]
	v_pk_fma_f32 v[80:81], v[54:55], v[86:87], v[80:81]
	v_pk_fma_f32 v[82:83], v[52:53], v[86:87], v[82:83]
	ds_read_u16 v86, v88 offset:32768
	ds_read_u16 v87, v89 offset:32768
	s_waitcnt lgkmcnt(1)
	v_lshlrev_b32_e32 v86, 16, v86
	s_waitcnt lgkmcnt(0)
	v_lshlrev_b32_e32 v87, 16, v87
	v_pk_fma_f32 v[72:73], v[64:65], v[86:87], v[72:73]
	v_pk_fma_f32 v[74:75], v[62:63], v[86:87], v[74:75]
	v_pk_fma_f32 v[76:77], v[60:61], v[86:87], v[76:77]
	v_pk_fma_f32 v[78:79], v[58:59], v[86:87], v[78:79]
	v_pk_fma_f32 v[80:81], v[56:57], v[86:87], v[80:81]
	v_pk_fma_f32 v[82:83], v[54:55], v[86:87], v[82:83]
	ds_read_u16 v86, v88 offset:33792
	ds_read_u16 v87, v89 offset:33792
	s_waitcnt lgkmcnt(1)
	v_lshlrev_b32_e32 v86, 16, v86
	s_waitcnt lgkmcnt(0)
	v_lshlrev_b32_e32 v87, 16, v87
	v_pk_fma_f32 v[74:75], v[64:65], v[86:87], v[74:75]
	v_pk_fma_f32 v[76:77], v[62:63], v[86:87], v[76:77]
	v_pk_fma_f32 v[78:79], v[60:61], v[86:87], v[78:79]
	v_pk_fma_f32 v[80:81], v[58:59], v[86:87], v[80:81]
	v_pk_fma_f32 v[82:83], v[56:57], v[86:87], v[82:83]
	ds_read_u16 v86, v88 offset:34816
	ds_read_u16 v87, v89 offset:34816
	s_waitcnt lgkmcnt(1)
	v_lshlrev_b32_e32 v86, 16, v86
	s_waitcnt lgkmcnt(0)
	v_lshlrev_b32_e32 v87, 16, v87
	v_pk_fma_f32 v[76:77], v[64:65], v[86:87], v[76:77]
	v_pk_fma_f32 v[78:79], v[62:63], v[86:87], v[78:79]
	v_pk_fma_f32 v[80:81], v[60:61], v[86:87], v[80:81]
	v_pk_fma_f32 v[82:83], v[58:59], v[86:87], v[82:83]
	ds_read_u16 v86, v88 offset:35840
	ds_read_u16 v87, v89 offset:35840
	s_waitcnt lgkmcnt(1)
	v_lshlrev_b32_e32 v86, 16, v86
	s_waitcnt lgkmcnt(0)
	v_lshlrev_b32_e32 v87, 16, v87
	v_pk_fma_f32 v[78:79], v[64:65], v[86:87], v[78:79]
	v_pk_fma_f32 v[80:81], v[62:63], v[86:87], v[80:81]
	v_pk_fma_f32 v[82:83], v[60:61], v[86:87], v[82:83]
	ds_read_u16 v86, v88 offset:36864
	ds_read_u16 v87, v89 offset:36864
	s_waitcnt lgkmcnt(1)
	v_lshlrev_b32_e32 v86, 16, v86
	s_waitcnt lgkmcnt(0)
	v_lshlrev_b32_e32 v87, 16, v87
	v_pk_fma_f32 v[80:81], v[64:65], v[86:87], v[80:81]
	v_pk_fma_f32 v[82:83], v[62:63], v[86:87], v[82:83]
	ds_read_u16 v86, v88 offset:37888
	ds_read_u16 v87, v89 offset:37888
	s_waitcnt lgkmcnt(1)
	v_lshlrev_b32_e32 v86, 16, v86
	s_waitcnt lgkmcnt(0)
	v_lshlrev_b32_e32 v87, 16, v87
	v_pk_fma_f32 v[82:83], v[64:65], v[86:87], v[82:83]
	v_lshl_add_u32 v86, s26, 14, v85
	v_lshl_add_u32 v87, s27, 14, v85
	s_add_i32 s26, s26, 2
	s_add_i32 s27, s27, 2
	s_cmp_lg_u32 s28, 0
	ds_write_b32 v86, v68
	ds_write_b32 v87, v69
	ds_write_b32 v86, v70 offset:2048
	ds_write_b32 v87, v71 offset:2048
	ds_write_b32 v86, v72 offset:4096
	ds_write_b32 v87, v73 offset:4096
	ds_write_b32 v86, v74 offset:6144
	ds_write_b32 v87, v75 offset:6144
	ds_write_b32 v86, v76 offset:8192
	ds_write_b32 v87, v77 offset:8192
	ds_write_b32 v86, v78 offset:10240
	ds_write_b32 v87, v79 offset:10240
	ds_write_b32 v86, v80 offset:12288
	ds_write_b32 v87, v81 offset:12288
	ds_write_b32 v86, v82 offset:14336
	ds_write_b32 v87, v83 offset:14336
	s_cbranch_scc1 .LBB0_1209
	v_and_b32_e32 v4, 64, v248
	v_add_u32_e32 v4, 64, v4
	v_xor_b32_e32 v5, 1, v248
	v_cmp_lt_i32_e32 vcc, v5, v4
	v_and_b32_e32 v13, 63, v0
	v_ashrrev_i32_e32 v10, 4, v0
	v_cndmask_b32_e32 v5, v248, v5, vcc
	v_lshlrev_b32_e32 v9, 2, v5
	v_xor_b32_e32 v5, 2, v248
	v_cmp_lt_i32_e32 vcc, v5, v4
	v_xor_b32_e32 v14, 32, v248
	v_and_b32_e32 v12, -4, v10
	v_cndmask_b32_e32 v5, v248, v5, vcc
	v_lshlrev_b32_e32 v8, 2, v5
	v_xor_b32_e32 v5, 4, v248
	v_cmp_lt_i32_e32 vcc, v5, v4
	v_lshl_add_u32 v11, v13, 2, s25
	s_waitcnt lgkmcnt(0)
	v_cndmask_b32_e32 v5, v248, v5, vcc
	v_lshlrev_b32_e32 v7, 2, v5
	v_xor_b32_e32 v5, 8, v248
	v_cmp_lt_i32_e32 vcc, v5, v4
	s_barrier
	s_nop 0
	v_cndmask_b32_e32 v5, v248, v5, vcc
	v_lshlrev_b32_e32 v6, 2, v5
	v_xor_b32_e32 v5, 16, v248
	v_cmp_lt_i32_e32 vcc, v5, v4
	s_nop 1
	v_cndmask_b32_e32 v5, v248, v5, vcc
	v_cmp_lt_i32_e32 vcc, v14, v4
	v_lshlrev_b32_e32 v5, 2, v5
	s_nop 0
	v_cndmask_b32_e32 v4, v248, v14, vcc
	v_cmp_eq_u32_e32 vcc, 0, v13
	v_lshl_add_u32 v13, v12, 11, v11
	ds_read2st64_b32 v[14:15], v13 offset1:1
	v_lshlrev_b32_e32 v4, 2, v4
	s_waitcnt lgkmcnt(0)
	v_add_f32_e32 v16, 0, v14
	v_mul_f32_e32 v17, v15, v15
	v_add_f32_e32 v16, v16, v15
	v_fmac_f32_e32 v17, v14, v14
	ds_read2st64_b32 v[14:15], v13 offset0:2 offset1:3
	s_waitcnt lgkmcnt(0)
	v_add_f32_e32 v16, v16, v14
	v_fmac_f32_e32 v17, v14, v14
	v_add_f32_e32 v16, v16, v15
	v_fmac_f32_e32 v17, v15, v15
	ds_read2st64_b32 v[14:15], v13 offset0:4 offset1:5
	s_waitcnt lgkmcnt(0)
	v_add_f32_e32 v16, v16, v14
	v_fmac_f32_e32 v17, v14, v14
	v_add_f32_e32 v16, v16, v15
	v_fmac_f32_e32 v17, v15, v15
	ds_read2st64_b32 v[14:15], v13 offset0:6 offset1:7
	s_waitcnt lgkmcnt(0)
	v_add_f32_e32 v13, v16, v14
	v_fmac_f32_e32 v17, v14, v14
	v_add_f32_e32 v13, v13, v15
	v_fmac_f32_e32 v17, v15, v15
	s_nop 1
	v_add_f32_dpp v13, v13, v13 quad_perm:[1,0,3,2] row_mask:0xf bank_mask:0xf
	v_add_f32_dpp v15, v17, v17 quad_perm:[1,0,3,2] row_mask:0xf bank_mask:0xf
	s_nop 1
	v_add_f32_dpp v13, v13, v13 quad_perm:[2,3,0,1] row_mask:0xf bank_mask:0xf
	v_add_f32_dpp v15, v15, v15 quad_perm:[2,3,0,1] row_mask:0xf bank_mask:0xf
	s_nop 1
	v_add_f32_dpp v13, v13, v13 row_half_mirror row_mask:0xf bank_mask:0xf
	v_add_f32_dpp v15, v15, v15 row_half_mirror row_mask:0xf bank_mask:0xf
	s_nop 1
	v_add_f32_dpp v13, v13, v13 row_mirror row_mask:0xf bank_mask:0xf
	v_add_f32_dpp v15, v15, v15 row_mirror row_mask:0xf bank_mask:0xf
	ds_bpermute_b32 v14, v5, v13
	ds_bpermute_b32 v16, v5, v15
	s_waitcnt lgkmcnt(1)
	v_add_f32_e32 v13, v13, v14
	s_waitcnt lgkmcnt(0)
	v_add_f32_e32 v15, v15, v16
	ds_bpermute_b32 v14, v4, v13
	ds_bpermute_b32 v16, v4, v15
	s_and_saveexec_b64 s[26:27], vcc
	s_cbranch_execz .LBB0_1212
	s_waitcnt lgkmcnt(1)
	v_add_f32_e32 v13, v13, v14
	v_mul_f32_e32 v14, 0x3b000000, v13
	s_waitcnt lgkmcnt(0)
	v_add_f32_e32 v15, v15, v16
	v_mul_f32_e32 v13, v14, v14
	s_mov_b32 s25, 0x3b000000
	v_fma_f32 v13, v15, s25, -v13
	v_max_f32_e32 v13, 0, v13
	v_add_f32_e32 v13, 0x358637bd, v13
	v_rsq_f32_e32 v15, v13
	v_lshl_add_u32 v13, v10, 3, 0
	v_add_u32_e32 v13, 0x20000, v13
	ds_write_b64 v13, v[14:15]
.LBB0_1212:
	s_or_b64 exec, exec, s[26:27]
	v_or_b32_e32 v13, 1, v12
	s_waitcnt lgkmcnt(0)
	v_lshl_add_u32 v16, v13, 11, v11
	ds_read2st64_b32 v[14:15], v16 offset1:1
	s_waitcnt lgkmcnt(0)
	v_add_f32_e32 v17, 0, v14
	v_mul_f32_e32 v18, v15, v15
	v_add_f32_e32 v17, v17, v15
	v_fmac_f32_e32 v18, v14, v14
	ds_read2st64_b32 v[14:15], v16 offset0:2 offset1:3
	s_waitcnt lgkmcnt(0)
	v_add_f32_e32 v17, v17, v14
	v_fmac_f32_e32 v18, v14, v14
	v_add_f32_e32 v17, v17, v15
	v_fmac_f32_e32 v18, v15, v15
	ds_read2st64_b32 v[14:15], v16 offset0:4 offset1:5
	s_waitcnt lgkmcnt(0)
	v_add_f32_e32 v17, v17, v14
	v_fmac_f32_e32 v18, v14, v14
	v_add_f32_e32 v17, v17, v15
	v_fmac_f32_e32 v18, v15, v15
	ds_read2st64_b32 v[14:15], v16 offset0:6 offset1:7
	s_waitcnt lgkmcnt(0)
	v_add_f32_e32 v16, v17, v14
	v_fmac_f32_e32 v18, v14, v14
	v_add_f32_e32 v14, v16, v15
	v_fmac_f32_e32 v18, v15, v15
	s_nop 1
	v_add_f32_dpp v14, v14, v14 quad_perm:[1,0,3,2] row_mask:0xf bank_mask:0xf
	v_add_f32_dpp v16, v18, v18 quad_perm:[1,0,3,2] row_mask:0xf bank_mask:0xf
	s_nop 1
	v_add_f32_dpp v14, v14, v14 quad_perm:[2,3,0,1] row_mask:0xf bank_mask:0xf
	v_add_f32_dpp v16, v16, v16 quad_perm:[2,3,0,1] row_mask:0xf bank_mask:0xf
	s_nop 1
	v_add_f32_dpp v14, v14, v14 row_half_mirror row_mask:0xf bank_mask:0xf
	v_add_f32_dpp v16, v16, v16 row_half_mirror row_mask:0xf bank_mask:0xf
	s_nop 1
	v_add_f32_dpp v14, v14, v14 row_mirror row_mask:0xf bank_mask:0xf
	v_add_f32_dpp v16, v16, v16 row_mirror row_mask:0xf bank_mask:0xf
	ds_bpermute_b32 v15, v5, v14
	ds_bpermute_b32 v17, v5, v16
	s_waitcnt lgkmcnt(1)
	v_add_f32_e32 v14, v14, v15
	s_waitcnt lgkmcnt(0)
	v_add_f32_e32 v16, v16, v17
	ds_bpermute_b32 v15, v4, v14
	ds_bpermute_b32 v17, v4, v16
	s_and_saveexec_b64 s[26:27], vcc
	s_cbranch_execz .LBB0_1214
	s_waitcnt lgkmcnt(1)
	v_add_f32_e32 v14, v14, v15
	v_mul_f32_e32 v14, 0x3b000000, v14
	s_waitcnt lgkmcnt(0)
	v_add_f32_e32 v16, v16, v17
	v_mul_f32_e32 v15, v14, v14
	s_mov_b32 s25, 0x3b000000
	v_fma_f32 v15, v16, s25, -v15
	v_max_f32_e32 v15, 0, v15
	v_add_f32_e32 v15, 0x358637bd, v15
	v_rsq_f32_e32 v15, v15
	v_lshl_add_u32 v13, v13, 3, 0
	v_add_u32_e32 v13, 0x20000, v13
	ds_write_b64 v13, v[14:15]
.LBB0_1214:
	s_or_b64 exec, exec, s[26:27]
	v_or_b32_e32 v12, 2, v12
	v_lshl_add_u32 v13, v12, 11, v11
	s_waitcnt lgkmcnt(1)
	ds_read2st64_b32 v[14:15], v13 offset1:1
	s_waitcnt lgkmcnt(0)
	v_add_f32_e32 v16, 0, v14
	v_mul_f32_e32 v17, v15, v15
	v_add_f32_e32 v16, v16, v15
	v_fmac_f32_e32 v17, v14, v14
	ds_read2st64_b32 v[14:15], v13 offset0:2 offset1:3
	s_waitcnt lgkmcnt(0)
	v_add_f32_e32 v16, v16, v14
	v_fmac_f32_e32 v17, v14, v14
	v_add_f32_e32 v16, v16, v15
	v_fmac_f32_e32 v17, v15, v15
	ds_read2st64_b32 v[14:15], v13 offset0:4 offset1:5
	s_waitcnt lgkmcnt(0)
	v_add_f32_e32 v16, v16, v14
	v_fmac_f32_e32 v17, v14, v14
	v_add_f32_e32 v16, v16, v15
	v_fmac_f32_e32 v17, v15, v15
	ds_read2st64_b32 v[14:15], v13 offset0:6 offset1:7
	s_waitcnt lgkmcnt(0)
	v_add_f32_e32 v13, v16, v14
	v_fmac_f32_e32 v17, v14, v14
	v_add_f32_e32 v13, v13, v15
	v_fmac_f32_e32 v17, v15, v15
	s_nop 1
	v_add_f32_dpp v13, v13, v13 quad_perm:[1,0,3,2] row_mask:0xf bank_mask:0xf
	v_add_f32_dpp v15, v17, v17 quad_perm:[1,0,3,2] row_mask:0xf bank_mask:0xf
	s_nop 1
	v_add_f32_dpp v13, v13, v13 quad_perm:[2,3,0,1] row_mask:0xf bank_mask:0xf
	v_add_f32_dpp v15, v15, v15 quad_perm:[2,3,0,1] row_mask:0xf bank_mask:0xf
	s_nop 1
	v_add_f32_dpp v13, v13, v13 row_half_mirror row_mask:0xf bank_mask:0xf
	v_add_f32_dpp v15, v15, v15 row_half_mirror row_mask:0xf bank_mask:0xf
	s_nop 1
	v_add_f32_dpp v13, v13, v13 row_mirror row_mask:0xf bank_mask:0xf
	v_add_f32_dpp v15, v15, v15 row_mirror row_mask:0xf bank_mask:0xf
	ds_bpermute_b32 v14, v5, v13
	ds_bpermute_b32 v16, v5, v15
	s_waitcnt lgkmcnt(1)
	v_add_f32_e32 v13, v13, v14
	s_waitcnt lgkmcnt(0)
	v_add_f32_e32 v15, v15, v16
	ds_bpermute_b32 v14, v4, v13
	ds_bpermute_b32 v16, v4, v15
	s_and_saveexec_b64 s[26:27], vcc
	s_cbranch_execz .LBB0_1216
	s_waitcnt lgkmcnt(1)
	v_add_f32_e32 v13, v13, v14
	v_mul_f32_e32 v14, 0x3b000000, v13
	s_waitcnt lgkmcnt(0)
	v_add_f32_e32 v15, v15, v16
	v_mul_f32_e32 v13, v14, v14
	s_mov_b32 s25, 0x3b000000
	v_fma_f32 v13, v15, s25, -v13
	v_max_f32_e32 v13, 0, v13
	v_add_f32_e32 v13, 0x358637bd, v13
	v_rsq_f32_e32 v15, v13
	v_lshl_add_u32 v12, v12, 3, 0
	v_add_u32_e32 v12, 0x20000, v12
	ds_write_b64 v12, v[14:15]
.LBB0_1216:
	s_or_b64 exec, exec, s[26:27]
	v_or_b32_e32 v10, 3, v10
	v_lshl_add_u32 v11, v10, 11, v11
	ds_read2st64_b32 v[12:13], v11 offset1:1
	s_waitcnt lgkmcnt(0)
	v_add_f32_e32 v14, 0, v12
	v_mul_f32_e32 v15, v13, v13
	v_add_f32_e32 v14, v14, v13
	v_fmac_f32_e32 v15, v12, v12
	ds_read2st64_b32 v[12:13], v11 offset0:2 offset1:3
	s_waitcnt lgkmcnt(0)
	v_add_f32_e32 v14, v14, v12
	v_fmac_f32_e32 v15, v12, v12
	v_add_f32_e32 v14, v14, v13
	v_fmac_f32_e32 v15, v13, v13
	ds_read2st64_b32 v[12:13], v11 offset0:4 offset1:5
	s_waitcnt lgkmcnt(0)
	v_add_f32_e32 v14, v14, v12
	v_fmac_f32_e32 v15, v12, v12
	v_add_f32_e32 v14, v14, v13
	v_fmac_f32_e32 v15, v13, v13
	ds_read2st64_b32 v[12:13], v11 offset0:6 offset1:7
	s_waitcnt lgkmcnt(0)
	v_add_f32_e32 v11, v14, v12
	v_fmac_f32_e32 v15, v12, v12
	v_add_f32_e32 v11, v11, v13
	v_fmac_f32_e32 v15, v13, v13
	s_nop 1
	v_add_f32_dpp v11, v11, v11 quad_perm:[1,0,3,2] row_mask:0xf bank_mask:0xf
	v_add_f32_dpp v9, v15, v15 quad_perm:[1,0,3,2] row_mask:0xf bank_mask:0xf
	s_nop 1
	v_add_f32_dpp v11, v11, v11 quad_perm:[2,3,0,1] row_mask:0xf bank_mask:0xf
	v_add_f32_dpp v8, v9, v9 quad_perm:[2,3,0,1] row_mask:0xf bank_mask:0xf
	s_nop 1
	v_add_f32_dpp v11, v11, v11 row_half_mirror row_mask:0xf bank_mask:0xf
	v_add_f32_dpp v7, v8, v8 row_half_mirror row_mask:0xf bank_mask:0xf
	s_nop 1
	v_add_f32_dpp v11, v11, v11 row_mirror row_mask:0xf bank_mask:0xf
	v_add_f32_dpp v6, v7, v7 row_mirror row_mask:0xf bank_mask:0xf
	ds_bpermute_b32 v12, v5, v11
	ds_bpermute_b32 v5, v5, v6
	s_waitcnt lgkmcnt(1)
	v_add_f32_e32 v11, v11, v12
	s_waitcnt lgkmcnt(0)
	v_add_f32_e32 v5, v6, v5
	ds_bpermute_b32 v12, v4, v11
	ds_bpermute_b32 v4, v4, v5
	s_and_saveexec_b64 s[26:27], vcc
	s_cbranch_execz .LBB0_1218
	s_waitcnt lgkmcnt(0)
	v_add_f32_e32 v5, v5, v4
	v_add_f32_e32 v4, v11, v12
	v_mul_f32_e32 v4, 0x3b000000, v4
	v_mul_f32_e32 v6, v4, v4
	s_mov_b32 s25, 0x3b000000
	v_fma_f32 v5, v5, s25, -v6
	v_max_f32_e32 v5, 0, v5
	v_add_f32_e32 v5, 0x358637bd, v5
	v_rsq_f32_e32 v5, v5
	v_lshl_add_u32 v6, v10, 3, 0
	v_add_u32_e32 v6, 0x20000, v6
	ds_write_b64 v6, v[4:5]

.LBB0_1643:
	s_and_b64 vcc, exec, s[48:49]
	s_cbranch_vccnz .LBB0_1624
	s_waitcnt vmcnt(3)
	v_pk_mul_f32 v[64:65], v[62:63], v[62:63]
	v_pk_mul_f32 v[66:67], v[60:61], v[60:61]
	s_nop 0
	v_pk_mov_b32 v[88:89], v[66:67], v[64:65] op_sel:[1,0]
	v_mov_b32_e32 v67, v65
	v_pk_add_f32 v[64:65], v[88:89], v[66:67]
	s_waitcnt vmcnt(2)
	v_pk_mul_f32 v[66:67], v[58:59], v[58:59]
	v_pk_add_f32 v[64:65], v[64:65], v[64:65] op_sel_hi:[0,1]
	v_pk_mul_f32 v[88:89], v[56:57], v[56:57]
	s_waitcnt vmcnt(1)
	v_mul_f32_e32 v64, v52, v52
	v_pk_mov_b32 v[90:91], v[88:89], v[66:67] op_sel:[1,0]
	v_mov_b32_e32 v89, v67
	v_pk_add_f32 v[66:67], v[90:91], v[88:89]
	v_pk_fma_f32 v[88:89], v[52:53], v[52:53], v[64:65] op_sel_hi:[1,1,0]
	v_mul_f32_e32 v64, v54, v54
	v_pk_add_f32 v[66:67], v[66:67], v[66:67] op_sel_hi:[0,1]
	v_pk_fma_f32 v[90:91], v[54:55], v[54:55], v[64:65] op_sel_hi:[1,1,0]
	s_waitcnt vmcnt(0)
	v_mul_f32_e32 v88, v48, v48
	v_mul_f32_e32 v90, v49, v49
	v_mul_f32_e32 v66, v50, v50
	v_mul_f32_e32 v64, v51, v51
	v_pk_add_f32 v[88:89], v[88:89], v[90:91]
	v_pk_add_f32 v[64:65], v[66:67], v[64:65]
	v_xor_b32_e32 v66, 1, v248
	v_pk_add_f32 v[64:65], v[88:89], v[64:65]
	s_nop 0
	v_add_f32_e32 v64, v64, v65
	v_and_b32_e32 v65, 64, v248
	v_add_u32_e32 v65, 64, v65
	v_cmp_lt_i32_e32 vcc, v66, v65
	s_nop 1
	v_cndmask_b32_e32 v66, v248, v66, vcc
	v_lshlrev_b32_e32 v73, 2, v66
	s_waitcnt lgkmcnt(0)
	s_nop 1
	v_add_f32_dpp v64, v64, v64 quad_perm:[1,0,3,2] row_mask:0xf bank_mask:0xf
	v_xor_b32_e32 v66, 2, v248
	v_cmp_lt_i32_e32 vcc, v66, v65
	s_nop 1
	v_cndmask_b32_e32 v66, v248, v66, vcc
	v_lshlrev_b32_e32 v77, 2, v66
	s_waitcnt lgkmcnt(0)
	s_nop 1
	v_add_f32_dpp v64, v64, v64 quad_perm:[2,3,0,1] row_mask:0xf bank_mask:0xf
	v_xor_b32_e32 v66, 4, v248
	v_cmp_lt_i32_e32 vcc, v66, v65
	s_nop 1
	v_cndmask_b32_e32 v66, v248, v66, vcc
	v_lshlrev_b32_e32 v79, 2, v66
	s_waitcnt lgkmcnt(0)
	s_nop 1
	v_add_f32_dpp v64, v64, v64 row_half_mirror row_mask:0xf bank_mask:0xf
	v_xor_b32_e32 v66, 8, v248
	v_cmp_lt_i32_e32 vcc, v66, v65
	s_nop 1
	v_cndmask_b32_e32 v66, v248, v66, vcc
	v_lshlrev_b32_e32 v81, 2, v66
	s_waitcnt lgkmcnt(0)
	s_nop 1
	v_add_f32_dpp v64, v64, v64 row_mirror row_mask:0xf bank_mask:0xf
	v_xor_b32_e32 v66, 16, v248
	v_cmp_lt_i32_e32 vcc, v66, v65
	s_nop 1
	v_cndmask_b32_e32 v66, v248, v66, vcc
	v_lshlrev_b32_e32 v90, 2, v66
	ds_bpermute_b32 v66, v90, v64
	s_waitcnt lgkmcnt(0)
	v_add_f32_e32 v88, v64, v66
	v_xor_b32_e32 v64, 32, v248
	v_cmp_lt_i32_e32 vcc, v64, v65
	s_nop 1
	v_cndmask_b32_e32 v64, v248, v64, vcc
	v_lshlrev_b32_e32 v91, 2, v64
	global_load_dwordx4 v[64:67], v[74:75], off
	ds_bpermute_b32 v89, v91, v88
	s_and_b64 vcc, exec, s[42:43]
	s_cbranch_vccnz .LBB0_1646
	global_store_dwordx4 v[84:85], v[60:63], off offset:-3072

.LBB0_1652:
	v_lshlrev_b32_e32 v56, 2, v80
	global_load_dwordx4 v[62:65], v56, s[18:19]
	global_load_dwordx4 v[94:97], v56, s[16:17]
	v_mov_b32_e32 v58, v88
	v_mov_b32_e32 v59, v88
	v_pk_mul_f32 v[50:51], v[50:51], v[58:59]
	v_pk_mul_f32 v[48:49], v[48:49], v[88:89]
	s_waitcnt vmcnt(2)
	v_pk_mul_f32 v[50:51], v[50:51], v[54:55]
	v_pk_mul_f32 v[48:49], v[48:49], v[52:53]
	v_readlane_b32 s15, v254, 31
	s_add_i32 s16, s15, s14
	s_cmpk_gt_i32 s16, 0x1fff
	s_waitcnt vmcnt(0)
	v_pk_add_f32 v[52:53], v[96:97], 1.0 op_sel_hi:[1,0]
	v_pk_add_f32 v[54:55], v[94:95], 1.0 op_sel_hi:[1,0]
	v_pk_fma_f32 v[50:51], v[50:51], v[52:53], v[64:65]
	v_pk_fma_f32 v[48:49], v[48:49], v[54:55], v[62:63]
	s_nop 0
	v_cvt_pk_bf16_f32 v48, v48, v49
	v_cvt_pk_bf16_f32 v49, v50, v51
	v_add_co_u32_e32 v50, vcc, 0xf7c01000, v86
	s_nop 1
	v_addc_co_u32_e32 v51, vcc, -1, v87, vcc
	global_store_dwordx2 v[50:51], v[48:49], off offset:-2560
	s_cbranch_scc1 .LBB0_1624
	v_pk_mul_f32 v[48:49], v[46:47], v[46:47]
	v_pk_mul_f32 v[50:51], v[44:45], v[44:45]
	s_ashr_i32 s17, s16, 31
	v_pk_mov_b32 v[52:53], v[50:51], v[48:49] op_sel:[1,0]
	v_mov_b32_e32 v51, v49
	v_pk_add_f32 v[48:49], v[52:53], v[50:51]
	v_pk_mul_f32 v[50:51], v[42:43], v[42:43]
	v_pk_add_f32 v[48:49], v[48:49], v[48:49] op_sel_hi:[0,1]
	v_pk_mul_f32 v[52:53], v[40:41], v[40:41]
	v_mul_f32_e32 v48, v36, v36
	v_pk_mov_b32 v[54:55], v[52:53], v[50:51] op_sel:[1,0]
	v_mov_b32_e32 v53, v51
	v_pk_add_f32 v[50:51], v[54:55], v[52:53]
	v_pk_fma_f32 v[52:53], v[36:37], v[36:37], v[48:49] op_sel_hi:[1,1,0]
	v_mul_f32_e32 v48, v38, v38
	v_pk_add_f32 v[50:51], v[50:51], v[50:51] op_sel_hi:[0,1]
	v_pk_fma_f32 v[54:55], v[38:39], v[38:39], v[48:49] op_sel_hi:[1,1,0]
	v_mul_f32_e32 v52, v32, v32
	v_mul_f32_e32 v54, v33, v33
	v_mul_f32_e32 v50, v34, v34
	v_mul_f32_e32 v48, v35, v35
	v_pk_add_f32 v[52:53], v[52:53], v[54:55]
	v_pk_add_f32 v[48:49], v[50:51], v[48:49]
	s_lshl_b64 s[18:19], s[16:17], 12
	v_pk_add_f32 v[48:49], v[52:53], v[48:49]
	v_lshl_add_u64 v[52:53], v[68:69], 0, s[18:19]
	v_add_f32_e32 v48, v48, v49
	s_and_b64 vcc, exec, s[42:43]
	s_waitcnt lgkmcnt(0)
	s_nop 1
	v_add_f32_dpp v48, v48, v48 quad_perm:[1,0,3,2] row_mask:0xf bank_mask:0xf
	s_waitcnt lgkmcnt(0)
	s_nop 1
	v_add_f32_dpp v48, v48, v48 quad_perm:[2,3,0,1] row_mask:0xf bank_mask:0xf
	s_waitcnt lgkmcnt(0)
	s_nop 1
	v_add_f32_dpp v48, v48, v48 row_half_mirror row_mask:0xf bank_mask:0xf
	s_waitcnt lgkmcnt(0)
	s_nop 1
	v_add_f32_dpp v48, v48, v48 row_mirror row_mask:0xf bank_mask:0xf
	ds_bpermute_b32 v49, v90, v48
	s_waitcnt lgkmcnt(0)
	v_add_f32_e32 v54, v48, v49
	global_load_dwordx4 v[48:51], v[74:75], off
	ds_bpermute_b32 v55, v91, v54
	s_cbranch_vccnz .LBB0_1655
	global_store_dwordx4 v[52:53], v[44:47], off

.LBB0_1661:
	global_load_dwordx4 v[40:43], v56, s[20:21]
	global_load_dwordx4 v[44:47], v56, s[18:19]
	v_mov_b32_e32 v50, v54
	v_mov_b32_e32 v51, v54
	v_pk_mul_f32 v[32:33], v[32:33], v[54:55]
	v_pk_mul_f32 v[34:35], v[34:35], v[50:51]
	v_readlane_b32 s15, v254, 30
	s_waitcnt vmcnt(2)
	v_pk_mul_f32 v[32:33], v[32:33], v[36:37]
	v_pk_mul_f32 v[34:35], v[34:35], v[38:39]
	s_add_i32 s16, s15, s14
	s_cmpk_gt_i32 s16, 0x1fff
	s_waitcnt vmcnt(1)
	v_pk_add_f32 v[36:37], v[42:43], 1.0 op_sel_hi:[1,0]
	v_pk_add_f32 v[38:39], v[40:41], 1.0 op_sel_hi:[1,0]
	s_waitcnt vmcnt(0)
	v_pk_fma_f32 v[34:35], v[34:35], v[36:37], v[46:47]
	v_pk_fma_f32 v[32:33], v[32:33], v[38:39], v[44:45]
	s_nop 0
	v_cvt_pk_bf16_f32 v32, v32, v33
	v_cvt_pk_bf16_f32 v33, v34, v35
	global_store_dwordx2 v[48:49], v[32:33], off offset:1536
	s_cbranch_scc1 .LBB0_1624
	v_pk_mul_f32 v[32:33], v[30:31], v[30:31]
	v_pk_mul_f32 v[34:35], v[28:29], v[28:29]
	s_ashr_i32 s17, s16, 31
	v_pk_mov_b32 v[36:37], v[34:35], v[32:33] op_sel:[1,0]
	v_mov_b32_e32 v35, v33
	v_pk_add_f32 v[32:33], v[36:37], v[34:35]
	v_pk_mul_f32 v[34:35], v[26:27], v[26:27]
	v_pk_add_f32 v[32:33], v[32:33], v[32:33] op_sel_hi:[0,1]
	v_pk_mul_f32 v[36:37], v[24:25], v[24:25]
	v_mul_f32_e32 v32, v20, v20
	v_pk_mov_b32 v[38:39], v[36:37], v[34:35] op_sel:[1,0]
	v_mov_b32_e32 v37, v35
	v_pk_add_f32 v[34:35], v[38:39], v[36:37]
	v_pk_fma_f32 v[36:37], v[20:21], v[20:21], v[32:33] op_sel_hi:[1,1,0]
	v_mul_f32_e32 v32, v22, v22
	v_pk_add_f32 v[34:35], v[34:35], v[34:35] op_sel_hi:[0,1]
	v_pk_fma_f32 v[38:39], v[22:23], v[22:23], v[32:33] op_sel_hi:[1,1,0]
	v_mul_f32_e32 v36, v16, v16
	v_mul_f32_e32 v38, v17, v17
	v_mul_f32_e32 v34, v18, v18
	v_mul_f32_e32 v32, v19, v19
	v_pk_add_f32 v[36:37], v[36:37], v[38:39]
	v_pk_add_f32 v[32:33], v[34:35], v[32:33]
	s_lshl_b64 s[18:19], s[16:17], 12
	v_pk_add_f32 v[32:33], v[36:37], v[32:33]
	v_lshl_add_u64 v[36:37], v[68:69], 0, s[18:19]
	v_add_f32_e32 v32, v32, v33
	s_and_b64 vcc, exec, s[42:43]
	s_waitcnt lgkmcnt(0)
	s_nop 1
	v_add_f32_dpp v32, v32, v32 quad_perm:[1,0,3,2] row_mask:0xf bank_mask:0xf
	s_waitcnt lgkmcnt(0)
	s_nop 1
	v_add_f32_dpp v32, v32, v32 quad_perm:[2,3,0,1] row_mask:0xf bank_mask:0xf
	s_waitcnt lgkmcnt(0)
	s_nop 1
	v_add_f32_dpp v32, v32, v32 row_half_mirror row_mask:0xf bank_mask:0xf
	s_waitcnt lgkmcnt(0)
	s_nop 1
	v_add_f32_dpp v32, v32, v32 row_mirror row_mask:0xf bank_mask:0xf
	ds_bpermute_b32 v33, v90, v32
	s_waitcnt lgkmcnt(0)
	v_add_f32_e32 v38, v32, v33
	global_load_dwordx4 v[32:35], v[74:75], off
	ds_bpermute_b32 v39, v91, v38
	s_cbranch_vccnz .LBB0_1664
	global_store_dwordx4 v[36:37], v[28:31], off

.LBB0_1670:
	global_load_dwordx4 v[24:27], v56, s[20:21]
	global_load_dwordx4 v[28:31], v56, s[18:19]
	v_mov_b32_e32 v34, v38
	v_mov_b32_e32 v35, v38
	v_pk_mul_f32 v[16:17], v[16:17], v[38:39]
	v_pk_mul_f32 v[18:19], v[18:19], v[34:35]
	v_readlane_b32 s15, v254, 32
	s_waitcnt vmcnt(2)
	v_pk_mul_f32 v[16:17], v[16:17], v[20:21]
	v_pk_mul_f32 v[18:19], v[18:19], v[22:23]
	s_add_i32 s16, s15, s14
	s_cmpk_gt_i32 s16, 0x1fff
	s_waitcnt vmcnt(1)
	v_pk_add_f32 v[20:21], v[26:27], 1.0 op_sel_hi:[1,0]
	v_pk_add_f32 v[22:23], v[24:25], 1.0 op_sel_hi:[1,0]
	s_waitcnt vmcnt(0)
	v_pk_fma_f32 v[18:19], v[18:19], v[20:21], v[30:31]
	v_pk_fma_f32 v[16:17], v[16:17], v[22:23], v[28:29]
	s_nop 0
	v_cvt_pk_bf16_f32 v16, v16, v17
	v_cvt_pk_bf16_f32 v17, v18, v19
	global_store_dwordx2 v[32:33], v[16:17], off offset:1536
	s_cbranch_scc1 .LBB0_1624
	v_pk_mul_f32 v[16:17], v[14:15], v[14:15]
	v_pk_mul_f32 v[18:19], v[12:13], v[12:13]
	s_ashr_i32 s17, s16, 31
	v_pk_mov_b32 v[20:21], v[18:19], v[16:17] op_sel:[1,0]
	v_mov_b32_e32 v19, v17
	v_pk_add_f32 v[16:17], v[20:21], v[18:19]
	v_pk_mul_f32 v[18:19], v[10:11], v[10:11]
	v_pk_add_f32 v[16:17], v[16:17], v[16:17] op_sel_hi:[0,1]
	v_pk_mul_f32 v[20:21], v[8:9], v[8:9]
	v_mul_f32_e32 v16, v4, v4
	v_pk_mov_b32 v[22:23], v[20:21], v[18:19] op_sel:[1,0]
	v_mov_b32_e32 v21, v19
	v_pk_add_f32 v[18:19], v[22:23], v[20:21]
	v_pk_fma_f32 v[20:21], v[4:5], v[4:5], v[16:17] op_sel_hi:[1,1,0]
	v_mul_f32_e32 v16, v6, v6
	v_pk_add_f32 v[18:19], v[18:19], v[18:19] op_sel_hi:[0,1]
	v_pk_fma_f32 v[22:23], v[6:7], v[6:7], v[16:17] op_sel_hi:[1,1,0]
	v_mul_f32_e32 v20, v0, v0
	v_mul_f32_e32 v22, v1, v1
	v_mul_f32_e32 v18, v2, v2
	v_mul_f32_e32 v16, v3, v3
	v_pk_add_f32 v[20:21], v[20:21], v[22:23]
	v_pk_add_f32 v[16:17], v[18:19], v[16:17]
	s_lshl_b64 s[18:19], s[16:17], 12
	v_pk_add_f32 v[16:17], v[20:21], v[16:17]
	v_lshl_add_u64 v[20:21], v[68:69], 0, s[18:19]
	v_add_f32_e32 v16, v16, v17
	s_and_b64 vcc, exec, s[42:43]
	s_waitcnt lgkmcnt(0)
	s_nop 1
	v_add_f32_dpp v16, v16, v16 quad_perm:[1,0,3,2] row_mask:0xf bank_mask:0xf
	s_waitcnt lgkmcnt(0)
	s_nop 1
	v_add_f32_dpp v16, v16, v16 quad_perm:[2,3,0,1] row_mask:0xf bank_mask:0xf
	s_waitcnt lgkmcnt(0)
	s_nop 1
	v_add_f32_dpp v16, v16, v16 row_half_mirror row_mask:0xf bank_mask:0xf
	s_waitcnt lgkmcnt(0)
	s_nop 1
	v_add_f32_dpp v16, v16, v16 row_mirror row_mask:0xf bank_mask:0xf
	ds_bpermute_b32 v17, v90, v16
	s_waitcnt lgkmcnt(0)
	v_add_f32_e32 v22, v16, v17
	global_load_dwordx4 v[16:19], v[74:75], off
	ds_bpermute_b32 v23, v91, v22
	s_cbranch_vccnz .LBB0_1673
	global_store_dwordx4 v[20:21], v[12:15], off

.LBB0_1998:
	s_and_b64 vcc, exec, s[46:47]
	s_cbranch_vccnz .LBB0_1979
	s_waitcnt vmcnt(0)
	v_pk_mul_f32 v[64:65], v[62:63], v[62:63]
	v_pk_mul_f32 v[66:67], v[60:61], v[60:61]
	s_nop 0
	v_pk_mov_b32 v[94:95], v[66:67], v[64:65] op_sel:[1,0]
	v_mov_b32_e32 v67, v65
	v_pk_add_f32 v[64:65], v[94:95], v[66:67]
	v_pk_mul_f32 v[66:67], v[58:59], v[58:59]
	v_pk_add_f32 v[64:65], v[64:65], v[64:65] op_sel_hi:[0,1]
	v_pk_mul_f32 v[94:95], v[56:57], v[56:57]
	v_mul_f32_e32 v64, v52, v52
	v_pk_mov_b32 v[96:97], v[94:95], v[66:67] op_sel:[1,0]
	v_mov_b32_e32 v95, v67
	v_pk_add_f32 v[66:67], v[96:97], v[94:95]
	v_pk_fma_f32 v[94:95], v[52:53], v[52:53], v[64:65] op_sel_hi:[1,1,0]
	v_mul_f32_e32 v64, v54, v54
	v_pk_add_f32 v[66:67], v[66:67], v[66:67] op_sel_hi:[0,1]
	v_pk_fma_f32 v[96:97], v[54:55], v[54:55], v[64:65] op_sel_hi:[1,1,0]
	v_mul_f32_e32 v94, v48, v48
	v_mul_f32_e32 v96, v49, v49
	v_mul_f32_e32 v66, v50, v50
	v_mul_f32_e32 v64, v51, v51
	v_pk_add_f32 v[94:95], v[94:95], v[96:97]
	v_pk_add_f32 v[64:65], v[66:67], v[64:65]
	v_xor_b32_e32 v66, 1, v248
	v_pk_add_f32 v[64:65], v[94:95], v[64:65]
	s_nop 0
	v_add_f32_e32 v64, v64, v65
	v_and_b32_e32 v65, 64, v248
	v_add_u32_e32 v65, 64, v65
	v_cmp_lt_i32_e32 vcc, v66, v65
	s_nop 1
	v_cndmask_b32_e32 v66, v248, v66, vcc
	v_lshlrev_b32_e32 v73, 2, v66
	s_waitcnt lgkmcnt(0)
	s_nop 1
	v_add_f32_dpp v64, v64, v64 quad_perm:[1,0,3,2] row_mask:0xf bank_mask:0xf
	v_xor_b32_e32 v66, 2, v248
	v_cmp_lt_i32_e32 vcc, v66, v65
	s_nop 1
	v_cndmask_b32_e32 v66, v248, v66, vcc
	v_lshlrev_b32_e32 v77, 2, v66
	s_waitcnt lgkmcnt(0)
	s_nop 1
	v_add_f32_dpp v64, v64, v64 quad_perm:[2,3,0,1] row_mask:0xf bank_mask:0xf
	v_xor_b32_e32 v66, 4, v248
	v_cmp_lt_i32_e32 vcc, v66, v65
	s_nop 1
	v_cndmask_b32_e32 v66, v248, v66, vcc
	v_lshlrev_b32_e32 v81, 2, v66
	s_waitcnt lgkmcnt(0)
	s_nop 1
	v_add_f32_dpp v64, v64, v64 row_half_mirror row_mask:0xf bank_mask:0xf
	v_xor_b32_e32 v66, 8, v248
	v_cmp_lt_i32_e32 vcc, v66, v65
	s_nop 1
	v_cndmask_b32_e32 v66, v248, v66, vcc
	v_lshlrev_b32_e32 v85, 2, v66
	s_waitcnt lgkmcnt(0)
	s_nop 1
	v_add_f32_dpp v64, v64, v64 row_mirror row_mask:0xf bank_mask:0xf
	v_xor_b32_e32 v66, 16, v248
	v_cmp_lt_i32_e32 vcc, v66, v65
	s_nop 1
	v_cndmask_b32_e32 v66, v248, v66, vcc
	v_lshlrev_b32_e32 v96, 2, v66
	ds_bpermute_b32 v66, v96, v64
	s_waitcnt lgkmcnt(0)
	v_add_f32_e32 v94, v64, v66
	v_xor_b32_e32 v64, 32, v248
	v_cmp_lt_i32_e32 vcc, v64, v65
	s_nop 1
	v_cndmask_b32_e32 v64, v248, v64, vcc
	v_lshlrev_b32_e32 v97, 2, v64
	global_load_dwordx4 v[64:67], v[74:75], off
	ds_bpermute_b32 v95, v97, v94
	s_and_b64 vcc, exec, s[42:43]
	s_cbranch_vccnz .LBB0_2001
	global_store_dwordx4 v[90:91], v[60:63], off offset:-3072

.LBB0_2007:
	v_lshlrev_b32_e32 v58, 2, v84
	global_load_dwordx4 v[62:65], v[64:65], off offset:3072
	v_mov_b32_e32 v56, v94
	global_load_dwordx4 v[100:103], v58, s[22:23]
	v_mov_b32_e32 v57, v94
	v_pk_mul_f32 v[50:51], v[50:51], v[56:57]
	v_pk_mul_f32 v[48:49], v[48:49], v[94:95]
	s_waitcnt vmcnt(2)
	v_pk_mul_f32 v[50:51], v[50:51], v[54:55]
	v_pk_mul_f32 v[48:49], v[48:49], v[52:53]
	v_readlane_b32 s21, v254, 31
	s_add_i32 s22, s21, s20
	s_cmpk_gt_i32 s22, 0x1fff
	s_waitcnt vmcnt(0)
	v_pk_add_f32 v[52:53], v[102:103], 1.0 op_sel_hi:[1,0]
	v_pk_add_f32 v[54:55], v[100:101], 1.0 op_sel_hi:[1,0]
	v_pk_fma_f32 v[50:51], v[50:51], v[52:53], v[64:65]
	v_pk_fma_f32 v[48:49], v[48:49], v[54:55], v[62:63]
	s_nop 0
	v_cvt_pk_bf16_f32 v48, v48, v49
	v_cvt_pk_bf16_f32 v49, v50, v51
	v_add_co_u32_e32 v50, vcc, 0xf7c01000, v92
	s_nop 1
	v_addc_co_u32_e32 v51, vcc, -1, v93, vcc
	global_store_dwordx2 v[50:51], v[48:49], off offset:-2560
	s_cbranch_scc1 .LBB0_1979
	v_pk_mul_f32 v[48:49], v[46:47], v[46:47]
	v_pk_mul_f32 v[50:51], v[44:45], v[44:45]
	s_ashr_i32 s23, s22, 31
	v_pk_mov_b32 v[52:53], v[50:51], v[48:49] op_sel:[1,0]
	v_mov_b32_e32 v51, v49
	v_pk_add_f32 v[48:49], v[52:53], v[50:51]
	v_pk_mul_f32 v[50:51], v[42:43], v[42:43]
	v_pk_add_f32 v[48:49], v[48:49], v[48:49] op_sel_hi:[0,1]
	v_pk_mul_f32 v[52:53], v[40:41], v[40:41]
	v_mul_f32_e32 v48, v36, v36
	v_pk_mov_b32 v[54:55], v[52:53], v[50:51] op_sel:[1,0]
	v_mov_b32_e32 v53, v51
	v_pk_add_f32 v[50:51], v[54:55], v[52:53]
	v_pk_fma_f32 v[52:53], v[36:37], v[36:37], v[48:49] op_sel_hi:[1,1,0]
	v_mul_f32_e32 v48, v38, v38
	v_pk_add_f32 v[50:51], v[50:51], v[50:51] op_sel_hi:[0,1]
	v_pk_fma_f32 v[54:55], v[38:39], v[38:39], v[48:49] op_sel_hi:[1,1,0]
	v_mul_f32_e32 v52, v32, v32
	v_mul_f32_e32 v54, v33, v33
	v_mul_f32_e32 v50, v34, v34
	v_mul_f32_e32 v48, v35, v35
	v_pk_add_f32 v[52:53], v[52:53], v[54:55]
	v_pk_add_f32 v[48:49], v[50:51], v[48:49]
	s_lshl_b64 s[24:25], s[22:23], 12
	v_pk_add_f32 v[48:49], v[52:53], v[48:49]
	v_lshl_add_u64 v[52:53], v[68:69], 0, s[24:25]
	v_add_f32_e32 v48, v48, v49
	s_and_b64 vcc, exec, s[42:43]
	s_waitcnt lgkmcnt(0)
	s_nop 1
	v_add_f32_dpp v48, v48, v48 quad_perm:[1,0,3,2] row_mask:0xf bank_mask:0xf
	s_waitcnt lgkmcnt(0)
	s_nop 1
	v_add_f32_dpp v48, v48, v48 quad_perm:[2,3,0,1] row_mask:0xf bank_mask:0xf
	s_waitcnt lgkmcnt(0)
	s_nop 1
	v_add_f32_dpp v48, v48, v48 row_half_mirror row_mask:0xf bank_mask:0xf
	s_waitcnt lgkmcnt(0)
	s_nop 1
	v_add_f32_dpp v48, v48, v48 row_mirror row_mask:0xf bank_mask:0xf
	ds_bpermute_b32 v49, v96, v48
	s_waitcnt lgkmcnt(0)
	v_add_f32_e32 v54, v48, v49
	global_load_dwordx4 v[48:51], v[74:75], off
	ds_bpermute_b32 v55, v97, v54
	s_cbranch_vccnz .LBB0_2010
	global_store_dwordx4 v[52:53], v[44:47], off

.LBB0_2016:
	global_load_dwordx4 v[40:43], v58, s[24:25]
	global_load_dwordx4 v[44:47], v[50:51], off offset:3072
	v_mov_b32_e32 v50, v54
	v_mov_b32_e32 v51, v54
	v_pk_mul_f32 v[32:33], v[32:33], v[54:55]
	v_pk_mul_f32 v[34:35], v[34:35], v[50:51]
	v_readlane_b32 s21, v254, 30
	s_waitcnt vmcnt(2)
	v_pk_mul_f32 v[32:33], v[32:33], v[36:37]
	v_pk_mul_f32 v[34:35], v[34:35], v[38:39]
	s_add_i32 s22, s21, s20
	s_cmpk_gt_i32 s22, 0x1fff
	s_waitcnt vmcnt(1)
	v_pk_add_f32 v[36:37], v[42:43], 1.0 op_sel_hi:[1,0]
	v_pk_add_f32 v[38:39], v[40:41], 1.0 op_sel_hi:[1,0]
	s_waitcnt vmcnt(0)
	v_pk_fma_f32 v[34:35], v[34:35], v[36:37], v[46:47]
	v_pk_fma_f32 v[32:33], v[32:33], v[38:39], v[44:45]
	s_nop 0
	v_cvt_pk_bf16_f32 v32, v32, v33
	v_cvt_pk_bf16_f32 v33, v34, v35
	global_store_dwordx2 v[48:49], v[32:33], off offset:1536
	s_cbranch_scc1 .LBB0_1979
	v_pk_mul_f32 v[32:33], v[30:31], v[30:31]
	v_pk_mul_f32 v[34:35], v[28:29], v[28:29]
	s_ashr_i32 s23, s22, 31
	v_pk_mov_b32 v[36:37], v[34:35], v[32:33] op_sel:[1,0]
	v_mov_b32_e32 v35, v33
	v_pk_add_f32 v[32:33], v[36:37], v[34:35]
	v_pk_mul_f32 v[34:35], v[26:27], v[26:27]
	v_pk_add_f32 v[32:33], v[32:33], v[32:33] op_sel_hi:[0,1]
	v_pk_mul_f32 v[36:37], v[24:25], v[24:25]
	v_mul_f32_e32 v32, v20, v20
	v_pk_mov_b32 v[38:39], v[36:37], v[34:35] op_sel:[1,0]
	v_mov_b32_e32 v37, v35
	v_pk_add_f32 v[34:35], v[38:39], v[36:37]
	v_pk_fma_f32 v[36:37], v[20:21], v[20:21], v[32:33] op_sel_hi:[1,1,0]
	v_mul_f32_e32 v32, v22, v22
	v_pk_add_f32 v[34:35], v[34:35], v[34:35] op_sel_hi:[0,1]
	v_pk_fma_f32 v[38:39], v[22:23], v[22:23], v[32:33] op_sel_hi:[1,1,0]
	v_mul_f32_e32 v36, v16, v16
	v_mul_f32_e32 v38, v17, v17
	v_mul_f32_e32 v34, v18, v18
	v_mul_f32_e32 v32, v19, v19
	v_pk_add_f32 v[36:37], v[36:37], v[38:39]
	v_pk_add_f32 v[32:33], v[34:35], v[32:33]
	s_lshl_b64 s[24:25], s[22:23], 12
	v_pk_add_f32 v[32:33], v[36:37], v[32:33]
	v_lshl_add_u64 v[36:37], v[68:69], 0, s[24:25]
	v_add_f32_e32 v32, v32, v33
	s_and_b64 vcc, exec, s[42:43]
	s_waitcnt lgkmcnt(0)
	s_nop 1
	v_add_f32_dpp v32, v32, v32 quad_perm:[1,0,3,2] row_mask:0xf bank_mask:0xf
	s_waitcnt lgkmcnt(0)
	s_nop 1
	v_add_f32_dpp v32, v32, v32 quad_perm:[2,3,0,1] row_mask:0xf bank_mask:0xf
	s_waitcnt lgkmcnt(0)
	s_nop 1
	v_add_f32_dpp v32, v32, v32 row_half_mirror row_mask:0xf bank_mask:0xf
	s_waitcnt lgkmcnt(0)
	s_nop 1
	v_add_f32_dpp v32, v32, v32 row_mirror row_mask:0xf bank_mask:0xf
	ds_bpermute_b32 v33, v96, v32
	s_waitcnt lgkmcnt(0)
	v_add_f32_e32 v38, v32, v33
	global_load_dwordx4 v[32:35], v[74:75], off
	ds_bpermute_b32 v39, v97, v38
	s_cbranch_vccnz .LBB0_2019
	global_store_dwordx4 v[36:37], v[28:31], off

.LBB0_2025:
	global_load_dwordx4 v[24:27], v58, s[24:25]
	global_load_dwordx4 v[28:31], v[34:35], off offset:3072
	v_mov_b32_e32 v34, v38
	v_mov_b32_e32 v35, v38
	v_pk_mul_f32 v[16:17], v[16:17], v[38:39]
	v_pk_mul_f32 v[18:19], v[18:19], v[34:35]
	v_readlane_b32 s21, v254, 32
	s_waitcnt vmcnt(2)
	v_pk_mul_f32 v[16:17], v[16:17], v[20:21]
	v_pk_mul_f32 v[18:19], v[18:19], v[22:23]
	s_add_i32 s22, s21, s20
	s_cmpk_gt_i32 s22, 0x1fff
	s_waitcnt vmcnt(1)
	v_pk_add_f32 v[20:21], v[26:27], 1.0 op_sel_hi:[1,0]
	v_pk_add_f32 v[22:23], v[24:25], 1.0 op_sel_hi:[1,0]
	s_waitcnt vmcnt(0)
	v_pk_fma_f32 v[18:19], v[18:19], v[20:21], v[30:31]
	v_pk_fma_f32 v[16:17], v[16:17], v[22:23], v[28:29]
	s_nop 0
	v_cvt_pk_bf16_f32 v16, v16, v17
	v_cvt_pk_bf16_f32 v17, v18, v19
	global_store_dwordx2 v[32:33], v[16:17], off offset:1536
	s_cbranch_scc1 .LBB0_1979
	v_pk_mul_f32 v[16:17], v[14:15], v[14:15]
	v_pk_mul_f32 v[18:19], v[12:13], v[12:13]
	s_ashr_i32 s23, s22, 31
	v_pk_mov_b32 v[20:21], v[18:19], v[16:17] op_sel:[1,0]
	v_mov_b32_e32 v19, v17
	v_pk_add_f32 v[16:17], v[20:21], v[18:19]
	v_pk_mul_f32 v[18:19], v[10:11], v[10:11]
	v_pk_add_f32 v[16:17], v[16:17], v[16:17] op_sel_hi:[0,1]
	v_pk_mul_f32 v[20:21], v[8:9], v[8:9]
	v_mul_f32_e32 v16, v4, v4
	v_pk_mov_b32 v[22:23], v[20:21], v[18:19] op_sel:[1,0]
	v_mov_b32_e32 v21, v19
	v_pk_add_f32 v[18:19], v[22:23], v[20:21]
	v_pk_fma_f32 v[20:21], v[4:5], v[4:5], v[16:17] op_sel_hi:[1,1,0]
	v_mul_f32_e32 v16, v6, v6
	v_pk_add_f32 v[18:19], v[18:19], v[18:19] op_sel_hi:[0,1]
	v_pk_fma_f32 v[22:23], v[6:7], v[6:7], v[16:17] op_sel_hi:[1,1,0]
	v_mul_f32_e32 v20, v0, v0
	v_mul_f32_e32 v22, v1, v1
	v_mul_f32_e32 v18, v2, v2
	v_mul_f32_e32 v16, v3, v3
	v_pk_add_f32 v[20:21], v[20:21], v[22:23]
	v_pk_add_f32 v[16:17], v[18:19], v[16:17]
	s_lshl_b64 s[24:25], s[22:23], 12
	v_pk_add_f32 v[16:17], v[20:21], v[16:17]
	v_lshl_add_u64 v[20:21], v[68:69], 0, s[24:25]
	v_add_f32_e32 v16, v16, v17
	s_and_b64 vcc, exec, s[42:43]
	s_waitcnt lgkmcnt(0)
	s_nop 1
	v_add_f32_dpp v16, v16, v16 quad_perm:[1,0,3,2] row_mask:0xf bank_mask:0xf
	s_waitcnt lgkmcnt(0)
	s_nop 1
	v_add_f32_dpp v16, v16, v16 quad_perm:[2,3,0,1] row_mask:0xf bank_mask:0xf
	s_waitcnt lgkmcnt(0)
	s_nop 1
	v_add_f32_dpp v16, v16, v16 row_half_mirror row_mask:0xf bank_mask:0xf
	s_waitcnt lgkmcnt(0)
	s_nop 1
	v_add_f32_dpp v16, v16, v16 row_mirror row_mask:0xf bank_mask:0xf
	ds_bpermute_b32 v17, v96, v16
	s_waitcnt lgkmcnt(0)
	v_add_f32_e32 v22, v16, v17
	global_load_dwordx4 v[16:19], v[74:75], off
	ds_bpermute_b32 v23, v97, v22
	s_cbranch_vccnz .LBB0_2028
	global_store_dwordx4 v[20:21], v[12:15], off

.LBB0_2057:
	s_and_b64 vcc, exec, s[24:25]
	s_cbranch_vccz .LBB0_2037
	s_andn2_b64 vcc, exec, s[22:23]
	s_cbranch_vccnz .LBB0_2037
	s_waitcnt vmcnt(3)
	v_pk_mul_f32 v[64:65], v[62:63], v[62:63]
	v_pk_mul_f32 v[66:67], v[60:61], v[60:61]
	v_readlane_b32 s4, v254, 31
	v_pk_mov_b32 v[78:79], v[66:67], v[64:65] op_sel:[1,0]
	v_mov_b32_e32 v67, v65
	v_pk_add_f32 v[64:65], v[78:79], v[66:67]
	s_waitcnt vmcnt(2)
	v_pk_mul_f32 v[66:67], v[58:59], v[58:59]
	v_pk_add_f32 v[64:65], v[64:65], v[64:65] op_sel_hi:[0,1]
	v_pk_mul_f32 v[78:79], v[56:57], v[56:57]
	s_waitcnt vmcnt(1)
	v_mul_f32_e32 v64, v52, v52
	v_pk_mov_b32 v[80:81], v[78:79], v[66:67] op_sel:[1,0]
	v_mov_b32_e32 v79, v67
	v_pk_add_f32 v[66:67], v[80:81], v[78:79]
	v_pk_fma_f32 v[78:79], v[52:53], v[52:53], v[64:65] op_sel_hi:[1,1,0]
	v_mul_f32_e32 v64, v54, v54
	v_pk_add_f32 v[66:67], v[66:67], v[66:67] op_sel_hi:[0,1]
	v_pk_fma_f32 v[80:81], v[54:55], v[54:55], v[64:65] op_sel_hi:[1,1,0]
	s_waitcnt vmcnt(0)
	v_mul_f32_e32 v78, v48, v48
	v_mul_f32_e32 v80, v49, v49
	v_mul_f32_e32 v66, v50, v50
	v_mul_f32_e32 v64, v51, v51
	v_pk_add_f32 v[78:79], v[78:79], v[80:81]
	v_pk_add_f32 v[64:65], v[66:67], v[64:65]
	v_xor_b32_e32 v66, 1, v248
	v_pk_add_f32 v[64:65], v[78:79], v[64:65]
	s_add_i32 s22, s4, s20
	v_add_f32_e32 v64, v64, v65
	v_and_b32_e32 v65, 64, v248
	v_add_u32_e32 v65, 64, v65
	v_cmp_lt_i32_e32 vcc, v66, v65
	s_cmpk_gt_i32 s22, 0x1fff
	s_nop 0
	v_cndmask_b32_e32 v66, v248, v66, vcc
	v_lshlrev_b32_e32 v79, 2, v66
	s_waitcnt lgkmcnt(0)
	s_nop 1
	v_add_f32_dpp v64, v64, v64 quad_perm:[1,0,3,2] row_mask:0xf bank_mask:0xf
	v_xor_b32_e32 v66, 2, v248
	v_cmp_lt_i32_e32 vcc, v66, v65
	s_nop 1
	v_cndmask_b32_e32 v66, v248, v66, vcc
	v_lshlrev_b32_e32 v80, 2, v66
	s_waitcnt lgkmcnt(0)
	s_nop 1
	v_add_f32_dpp v64, v64, v64 quad_perm:[2,3,0,1] row_mask:0xf bank_mask:0xf
	v_xor_b32_e32 v66, 4, v248
	v_cmp_lt_i32_e32 vcc, v66, v65
	s_nop 1
	v_cndmask_b32_e32 v66, v248, v66, vcc
	v_lshlrev_b32_e32 v81, 2, v66
	s_waitcnt lgkmcnt(0)
	s_nop 1
	v_add_f32_dpp v64, v64, v64 row_half_mirror row_mask:0xf bank_mask:0xf
	v_xor_b32_e32 v66, 8, v248
	v_cmp_lt_i32_e32 vcc, v66, v65
	s_nop 1
	v_cndmask_b32_e32 v66, v248, v66, vcc
	v_lshlrev_b32_e32 v82, 2, v66
	s_waitcnt lgkmcnt(0)
	s_nop 1
	v_add_f32_dpp v64, v64, v64 row_mirror row_mask:0xf bank_mask:0xf
	v_xor_b32_e32 v66, 16, v248
	v_cmp_lt_i32_e32 vcc, v66, v65
	s_nop 1
	v_cndmask_b32_e32 v66, v248, v66, vcc
	v_lshlrev_b32_e32 v83, 2, v66
	ds_bpermute_b32 v66, v83, v64
	s_waitcnt lgkmcnt(0)
	v_add_f32_e32 v64, v64, v66
	v_xor_b32_e32 v66, 32, v248
	v_cmp_lt_i32_e32 vcc, v66, v65
	s_nop 1
	v_cndmask_b32_e32 v65, v248, v66, vcc
	v_lshlrev_b32_e32 v84, 2, v65
	ds_bpermute_b32 v65, v84, v64
	s_waitcnt lgkmcnt(0)
	v_add_f32_e32 v64, v64, v65
	v_fmamk_f32 v64, v64, 0x3a800000, v245
	v_rsq_f32_e32 v78, v64
	global_load_dwordx4 v[64:67], v[72:73], off
	v_pk_mul_f32 v[60:61], v[60:61], v[78:79] op_sel_hi:[1,0]
	v_pk_mul_f32 v[62:63], v[62:63], v[78:79] op_sel_hi:[1,0]
	v_pk_mul_f32 v[58:59], v[58:59], v[78:79] op_sel_hi:[1,0]
	v_pk_mul_f32 v[56:57], v[56:57], v[78:79] op_sel_hi:[1,0]
	v_pk_mul_f32 v[54:55], v[54:55], v[78:79] op_sel_hi:[1,0]
	v_pk_mul_f32 v[52:53], v[52:53], v[78:79] op_sel_hi:[1,0]
	v_pk_mul_f32 v[50:51], v[50:51], v[78:79] op_sel_hi:[1,0]
	v_pk_mul_f32 v[48:49], v[48:49], v[78:79] op_sel_hi:[1,0]
	s_waitcnt vmcnt(0)
	v_pk_mul_f32 v[62:63], v[66:67], v[62:63]
	v_pk_mul_f32 v[60:61], v[64:65], v[60:61]
	global_store_dwordx4 v[74:75], v[60:63], off
	global_load_dwordx4 v[60:63], v[72:73], off offset:1024
	s_waitcnt vmcnt(0)
	v_pk_mul_f32 v[56:57], v[60:61], v[56:57]
	v_pk_mul_f32 v[58:59], v[62:63], v[58:59]
	global_store_dwordx4 v[74:75], v[56:59], off offset:1024
	global_load_dwordx4 v[56:59], v[72:73], off offset:2048
	s_waitcnt vmcnt(0)
	v_pk_mul_f32 v[52:53], v[56:57], v[52:53]
	v_pk_mul_f32 v[54:55], v[58:59], v[54:55]
	global_store_dwordx4 v[74:75], v[52:55], off offset:2048
	global_load_dwordx4 v[52:55], v[72:73], off offset:3072
	s_waitcnt vmcnt(0)
	v_pk_mul_f32 v[48:49], v[52:53], v[48:49]
	v_pk_mul_f32 v[50:51], v[54:55], v[50:51]
	global_store_dwordx4 v[74:75], v[48:51], off offset:3072
	s_cbranch_scc1 .LBB0_2037
	s_nop 0
	v_pk_mul_f32 v[48:49], v[46:47], v[46:47]
	v_pk_mul_f32 v[50:51], v[44:45], v[44:45]
	s_ashr_i32 s23, s22, 31
	v_pk_mov_b32 v[52:53], v[50:51], v[48:49] op_sel:[1,0]
	v_mov_b32_e32 v51, v49
	v_pk_add_f32 v[48:49], v[52:53], v[50:51]
	v_pk_mul_f32 v[50:51], v[42:43], v[42:43]
	v_pk_add_f32 v[48:49], v[48:49], v[48:49] op_sel_hi:[0,1]
	v_pk_mul_f32 v[52:53], v[40:41], v[40:41]
	v_mul_f32_e32 v48, v36, v36
	v_pk_mov_b32 v[54:55], v[52:53], v[50:51] op_sel:[1,0]
	v_mov_b32_e32 v53, v51
	v_pk_add_f32 v[50:51], v[54:55], v[52:53]
	v_pk_fma_f32 v[52:53], v[36:37], v[36:37], v[48:49] op_sel_hi:[1,1,0]
	v_mul_f32_e32 v48, v38, v38
	v_pk_add_f32 v[50:51], v[50:51], v[50:51] op_sel_hi:[0,1]
	v_pk_fma_f32 v[54:55], v[38:39], v[38:39], v[48:49] op_sel_hi:[1,1,0]
	v_mul_f32_e32 v52, v32, v32
	v_mul_f32_e32 v54, v33, v33
	v_mul_f32_e32 v50, v34, v34
	v_mul_f32_e32 v48, v35, v35
	v_pk_add_f32 v[52:53], v[52:53], v[54:55]
	v_pk_add_f32 v[48:49], v[50:51], v[48:49]
	s_lshl_b64 s[4:5], s[22:23], 12
	v_pk_add_f32 v[48:49], v[52:53], v[48:49]
	global_load_dwordx4 v[52:55], v[72:73], off
	v_add_f32_e32 v48, v48, v49
	s_waitcnt lgkmcnt(0)
	s_nop 1
	v_add_f32_dpp v48, v48, v48 quad_perm:[1,0,3,2] row_mask:0xf bank_mask:0xf
	s_waitcnt lgkmcnt(0)
	s_nop 1
	v_add_f32_dpp v48, v48, v48 quad_perm:[2,3,0,1] row_mask:0xf bank_mask:0xf
	s_waitcnt lgkmcnt(0)
	s_nop 1
	v_add_f32_dpp v48, v48, v48 row_half_mirror row_mask:0xf bank_mask:0xf
	s_waitcnt lgkmcnt(0)
	s_nop 1
	v_add_f32_dpp v48, v48, v48 row_mirror row_mask:0xf bank_mask:0xf
	ds_bpermute_b32 v49, v83, v48
	s_waitcnt lgkmcnt(0)
	v_add_f32_e32 v48, v48, v49
	ds_bpermute_b32 v49, v84, v48
	s_waitcnt lgkmcnt(0)
	v_add_f32_e32 v48, v48, v49
	v_fmamk_f32 v48, v48, 0x3a800000, v245
	v_rsq_f32_e32 v50, v48
	v_lshl_add_u64 v[48:49], v[68:69], 0, s[4:5]
	v_readlane_b32 s4, v254, 30
	s_add_i32 s22, s4, s20
	v_pk_mul_f32 v[44:45], v[44:45], v[50:51] op_sel_hi:[1,0]
	v_pk_mul_f32 v[46:47], v[46:47], v[50:51] op_sel_hi:[1,0]
	v_pk_mul_f32 v[42:43], v[42:43], v[50:51] op_sel_hi:[1,0]
	v_pk_mul_f32 v[40:41], v[40:41], v[50:51] op_sel_hi:[1,0]
	v_pk_mul_f32 v[38:39], v[38:39], v[50:51] op_sel_hi:[1,0]
	v_pk_mul_f32 v[36:37], v[36:37], v[50:51] op_sel_hi:[1,0]
	v_pk_mul_f32 v[34:35], v[34:35], v[50:51] op_sel_hi:[1,0]
	v_pk_mul_f32 v[32:33], v[32:33], v[50:51] op_sel_hi:[1,0]
	s_cmpk_gt_i32 s22, 0x1fff
	s_waitcnt vmcnt(0)
	v_pk_mul_f32 v[46:47], v[54:55], v[46:47]
	v_pk_mul_f32 v[44:45], v[52:53], v[44:45]
	global_store_dwordx4 v[48:49], v[44:47], off
	global_load_dwordx4 v[44:47], v[72:73], off offset:1024
	s_waitcnt vmcnt(0)
	v_pk_mul_f32 v[40:41], v[44:45], v[40:41]
	v_pk_mul_f32 v[42:43], v[46:47], v[42:43]
	global_store_dwordx4 v[48:49], v[40:43], off offset:1024
	global_load_dwordx4 v[40:43], v[72:73], off offset:2048
	s_waitcnt vmcnt(0)
	v_pk_mul_f32 v[36:37], v[40:41], v[36:37]
	v_pk_mul_f32 v[38:39], v[42:43], v[38:39]
	global_store_dwordx4 v[48:49], v[36:39], off offset:2048
	global_load_dwordx4 v[36:39], v[72:73], off offset:3072
	s_waitcnt vmcnt(0)
	v_pk_mul_f32 v[32:33], v[36:37], v[32:33]
	v_pk_mul_f32 v[34:35], v[38:39], v[34:35]
	global_store_dwordx4 v[48:49], v[32:35], off offset:3072
	s_cbranch_scc1 .LBB0_2037
	s_nop 0
	v_pk_mul_f32 v[32:33], v[30:31], v[30:31]
	v_pk_mul_f32 v[34:35], v[28:29], v[28:29]
	s_ashr_i32 s23, s22, 31
	v_pk_mov_b32 v[36:37], v[34:35], v[32:33] op_sel:[1,0]
	v_mov_b32_e32 v35, v33
	v_pk_add_f32 v[32:33], v[36:37], v[34:35]
	v_pk_mul_f32 v[34:35], v[26:27], v[26:27]
	v_pk_add_f32 v[32:33], v[32:33], v[32:33] op_sel_hi:[0,1]
	v_pk_mul_f32 v[36:37], v[24:25], v[24:25]
	v_mul_f32_e32 v32, v20, v20
	v_pk_mov_b32 v[38:39], v[36:37], v[34:35] op_sel:[1,0]
	v_mov_b32_e32 v37, v35
	v_pk_add_f32 v[34:35], v[38:39], v[36:37]
	v_pk_fma_f32 v[36:37], v[20:21], v[20:21], v[32:33] op_sel_hi:[1,1,0]
	v_mul_f32_e32 v32, v22, v22
	v_pk_add_f32 v[34:35], v[34:35], v[34:35] op_sel_hi:[0,1]
	v_pk_fma_f32 v[38:39], v[22:23], v[22:23], v[32:33] op_sel_hi:[1,1,0]
	v_mul_f32_e32 v36, v16, v16
	v_mul_f32_e32 v38, v17, v17
	v_mul_f32_e32 v34, v18, v18
	v_mul_f32_e32 v32, v19, v19
	v_pk_add_f32 v[36:37], v[36:37], v[38:39]
	v_pk_add_f32 v[32:33], v[34:35], v[32:33]
	s_lshl_b64 s[4:5], s[22:23], 12
	v_pk_add_f32 v[32:33], v[36:37], v[32:33]
	global_load_dwordx4 v[36:39], v[72:73], off
	v_add_f32_e32 v32, v32, v33
	s_waitcnt lgkmcnt(0)
	s_nop 1
	v_add_f32_dpp v32, v32, v32 quad_perm:[1,0,3,2] row_mask:0xf bank_mask:0xf
	s_waitcnt lgkmcnt(0)
	s_nop 1
	v_add_f32_dpp v32, v32, v32 quad_perm:[2,3,0,1] row_mask:0xf bank_mask:0xf
	s_waitcnt lgkmcnt(0)
	s_nop 1
	v_add_f32_dpp v32, v32, v32 row_half_mirror row_mask:0xf bank_mask:0xf
	s_waitcnt lgkmcnt(0)
	s_nop 1
	v_add_f32_dpp v32, v32, v32 row_mirror row_mask:0xf bank_mask:0xf
	ds_bpermute_b32 v33, v83, v32
	s_waitcnt lgkmcnt(0)
	v_add_f32_e32 v32, v32, v33
	ds_bpermute_b32 v33, v84, v32
	s_waitcnt lgkmcnt(0)
	v_add_f32_e32 v32, v32, v33
	v_fmamk_f32 v32, v32, 0x3a800000, v245
	v_rsq_f32_e32 v34, v32
	v_lshl_add_u64 v[32:33], v[68:69], 0, s[4:5]
	v_readlane_b32 s4, v254, 32
	s_add_i32 s22, s4, s20
	v_pk_mul_f32 v[28:29], v[28:29], v[34:35] op_sel_hi:[1,0]
	v_pk_mul_f32 v[30:31], v[30:31], v[34:35] op_sel_hi:[1,0]
	v_pk_mul_f32 v[26:27], v[26:27], v[34:35] op_sel_hi:[1,0]
	v_pk_mul_f32 v[24:25], v[24:25], v[34:35] op_sel_hi:[1,0]
	v_pk_mul_f32 v[22:23], v[22:23], v[34:35] op_sel_hi:[1,0]
	v_pk_mul_f32 v[20:21], v[20:21], v[34:35] op_sel_hi:[1,0]
	v_pk_mul_f32 v[18:19], v[18:19], v[34:35] op_sel_hi:[1,0]
	v_pk_mul_f32 v[16:17], v[16:17], v[34:35] op_sel_hi:[1,0]
	s_cmpk_gt_i32 s22, 0x1fff
	s_waitcnt vmcnt(0)
	v_pk_mul_f32 v[30:31], v[38:39], v[30:31]
	v_pk_mul_f32 v[28:29], v[36:37], v[28:29]
	global_store_dwordx4 v[32:33], v[28:31], off
	global_load_dwordx4 v[28:31], v[72:73], off offset:1024
	s_waitcnt vmcnt(0)
	v_pk_mul_f32 v[24:25], v[28:29], v[24:25]
	v_pk_mul_f32 v[26:27], v[30:31], v[26:27]
	global_store_dwordx4 v[32:33], v[24:27], off offset:1024
	global_load_dwordx4 v[24:27], v[72:73], off offset:2048
	s_waitcnt vmcnt(0)
	v_pk_mul_f32 v[20:21], v[24:25], v[20:21]
	v_pk_mul_f32 v[22:23], v[26:27], v[22:23]
	global_store_dwordx4 v[32:33], v[20:23], off offset:2048
	global_load_dwordx4 v[20:23], v[72:73], off offset:3072
	s_waitcnt vmcnt(0)
	v_pk_mul_f32 v[16:17], v[20:21], v[16:17]
	v_pk_mul_f32 v[18:19], v[22:23], v[18:19]
	global_store_dwordx4 v[32:33], v[16:19], off offset:3072
	s_cbranch_scc1 .LBB0_2037
	s_nop 0
	v_pk_mul_f32 v[16:17], v[14:15], v[14:15]
	v_pk_mul_f32 v[18:19], v[12:13], v[12:13]
	s_ashr_i32 s23, s22, 31
	v_pk_mov_b32 v[20:21], v[18:19], v[16:17] op_sel:[1,0]
	v_mov_b32_e32 v19, v17
	v_pk_add_f32 v[16:17], v[20:21], v[18:19]
	v_pk_mul_f32 v[18:19], v[10:11], v[10:11]
	v_pk_add_f32 v[16:17], v[16:17], v[16:17] op_sel_hi:[0,1]
	v_pk_mul_f32 v[20:21], v[8:9], v[8:9]
	v_mul_f32_e32 v16, v4, v4
	v_pk_mov_b32 v[22:23], v[20:21], v[18:19] op_sel:[1,0]
	v_mov_b32_e32 v21, v19
	v_pk_add_f32 v[18:19], v[22:23], v[20:21]
	v_pk_fma_f32 v[20:21], v[4:5], v[4:5], v[16:17] op_sel_hi:[1,1,0]
	v_mul_f32_e32 v16, v6, v6
	v_pk_add_f32 v[18:19], v[18:19], v[18:19] op_sel_hi:[0,1]
	v_pk_fma_f32 v[22:23], v[6:7], v[6:7], v[16:17] op_sel_hi:[1,1,0]
	v_mul_f32_e32 v20, v0, v0
	v_mul_f32_e32 v22, v1, v1
	v_mul_f32_e32 v18, v2, v2
	v_mul_f32_e32 v16, v3, v3
	v_pk_add_f32 v[20:21], v[20:21], v[22:23]
	v_pk_add_f32 v[16:17], v[18:19], v[16:17]
	s_lshl_b64 s[4:5], s[22:23], 12
	v_pk_add_f32 v[16:17], v[20:21], v[16:17]
	global_load_dwordx4 v[20:23], v[72:73], off
	v_add_f32_e32 v16, v16, v17
	s_waitcnt lgkmcnt(0)
	s_nop 1
	v_add_f32_dpp v16, v16, v16 quad_perm:[1,0,3,2] row_mask:0xf bank_mask:0xf
	s_waitcnt lgkmcnt(0)
	s_nop 1
	v_add_f32_dpp v16, v16, v16 quad_perm:[2,3,0,1] row_mask:0xf bank_mask:0xf
	s_waitcnt lgkmcnt(0)
	s_nop 1
	v_add_f32_dpp v16, v16, v16 row_half_mirror row_mask:0xf bank_mask:0xf
	s_waitcnt lgkmcnt(0)
	s_nop 1
	v_add_f32_dpp v16, v16, v16 row_mirror row_mask:0xf bank_mask:0xf
	ds_bpermute_b32 v17, v83, v16
	s_waitcnt lgkmcnt(0)
	v_add_f32_e32 v16, v16, v17
	ds_bpermute_b32 v17, v84, v16
	s_waitcnt lgkmcnt(0)
	v_add_f32_e32 v16, v16, v17
	v_fmamk_f32 v16, v16, 0x3a800000, v245
	v_rsq_f32_e32 v18, v16
	v_lshl_add_u64 v[16:17], v[68:69], 0, s[4:5]
	v_pk_mul_f32 v[12:13], v[12:13], v[18:19] op_sel_hi:[1,0]
	v_pk_mul_f32 v[14:15], v[14:15], v[18:19] op_sel_hi:[1,0]
	v_pk_mul_f32 v[10:11], v[10:11], v[18:19] op_sel_hi:[1,0]
	v_pk_mul_f32 v[8:9], v[8:9], v[18:19] op_sel_hi:[1,0]
	v_pk_mul_f32 v[6:7], v[6:7], v[18:19] op_sel_hi:[1,0]
	v_pk_mul_f32 v[4:5], v[4:5], v[18:19] op_sel_hi:[1,0]
	v_pk_mul_f32 v[2:3], v[2:3], v[18:19] op_sel_hi:[1,0]
	v_pk_mul_f32 v[0:1], v[0:1], v[18:19] op_sel_hi:[1,0]
	s_waitcnt vmcnt(0)
	v_pk_mul_f32 v[14:15], v[22:23], v[14:15]
	v_pk_mul_f32 v[12:13], v[20:21], v[12:13]
	global_store_dwordx4 v[16:17], v[12:15], off
	global_load_dwordx4 v[12:15], v[72:73], off offset:1024
	s_waitcnt vmcnt(0)
	v_pk_mul_f32 v[8:9], v[12:13], v[8:9]
	v_pk_mul_f32 v[10:11], v[14:15], v[10:11]
	global_store_dwordx4 v[16:17], v[8:11], off offset:1024
	global_load_dwordx4 v[8:11], v[72:73], off offset:2048
	s_waitcnt vmcnt(0)
	v_pk_mul_f32 v[4:5], v[8:9], v[4:5]
	v_pk_mul_f32 v[6:7], v[10:11], v[6:7]
	global_store_dwordx4 v[16:17], v[4:7], off offset:2048
	global_load_dwordx4 v[4:7], v[72:73], off offset:3072
	s_waitcnt vmcnt(0)
	v_pk_mul_f32 v[0:1], v[4:5], v[0:1]
	v_pk_mul_f32 v[2:3], v[6:7], v[2:3]
	global_store_dwordx4 v[16:17], v[0:3], off offset:3072
	s_branch .LBB0_2037
